# speedup vs baseline: 1.0138x; 1.0030x over previous
; #define LAS __attribute__((address_space(3)))
; __device__ __forceinline__ void ada_item(int it, const float* c, const float* cctx, const float* ada_w, const float* ada_b, float* mod, LAS float* sl) {
;     ...
;     for (int k = wid * 128; k < wid * 128 + 128; k += 4) {
;         const float w0 = W[(size_t)k * 6144], w1 = W[(size_t)(k + 1) * 6144], w2 = W[(size_t)(k + 2) * 6144], w3 = W[(size_t)(k + 3) * 6144];
; #pragma unroll
;         for (int j = 0; j < 9; ++j) { const f32x4 s = *(const LAS f32x4*)(sl + j * 1024 + k); acc[j] += s[0] * w0 + s[1] * w1 + s[2] * w2 + s[3] * w3; }
;     }
.LBB0_12:
	v_add_co_u32_e64 v166, s[6:7], s28, v154
	v_add_co_u32_e32 v164, vcc, 0xfffa6000, v154
	s_nop 0
	v_addc_co_u32_e64 v167, s[6:7], -1, v155, s[6:7]
	v_add_co_u32_e64 v168, s[6:7], s29, v154
	v_addc_co_u32_e32 v165, vcc, -1, v155, vcc
	s_nop 0
	v_addc_co_u32_e64 v169, s[6:7], -1, v155, s[6:7]
	v_add_co_u32_e64 v170, s[6:7], s30, v154
	v_add_co_u32_e32 v192, vcc, 0xfffac000, v154
	s_nop 0
	v_addc_co_u32_e64 v171, s[6:7], -1, v155, s[6:7]
	v_add_co_u32_e64 v172, s[6:7], s31, v154
	v_addc_co_u32_e32 v193, vcc, -1, v155, vcc
	s_nop 0
	v_addc_co_u32_e64 v173, s[6:7], -1, v155, s[6:7]
	v_add_co_u32_e64 v174, s[6:7], s33, v154
	v_add_co_u32_e32 v194, vcc, 0xfffb2000, v154
	s_nop 0
	v_addc_co_u32_e64 v175, s[6:7], -1, v155, s[6:7]
	v_add_co_u32_e64 v176, s[6:7], s34, v154
	ds_read_b128 v[18:21], v190
	ds_read_b128 v[14:17], v190 offset:16
	ds_read_b128 v[6:9], v190 offset:32
	ds_read_b128 v[2:5], v190 offset:48
	v_addc_co_u32_e64 v177, s[6:7], -1, v155, s[6:7]
	v_add_co_u32_e64 v178, s[6:7], s35, v154
	ds_read_b128 v[10:13], v190 offset:4096
	ds_read_b128 v[22:25], v190 offset:4112
	ds_read_b128 v[58:61], v190 offset:8192
	ds_read_b128 v[62:65], v190 offset:8208
	ds_read_b128 v[30:33], v190 offset:12288
	ds_read_b128 v[26:29], v190 offset:12304
	ds_read_b128 v[66:69], v190 offset:16384
	ds_read_b128 v[70:73], v190 offset:16400
	ds_read_b128 v[38:41], v190 offset:20480
	ds_read_b128 v[34:37], v190 offset:20496
	ds_read_b128 v[74:77], v190 offset:24576
	ds_read_b128 v[78:81], v190 offset:24592
	ds_read_b128 v[46:49], v190 offset:28672
	ds_read_b128 v[42:45], v190 offset:28688
	ds_read_b128 v[50:53], v190 offset:32768
	ds_read_b128 v[54:57], v190 offset:32784
	v_addc_co_u32_e64 v179, s[6:7], -1, v155, s[6:7]
	v_add_co_u32_e64 v180, s[6:7], s36, v154
	global_load_dword v148, v[154:155], off nt
	s_nop 0
	v_addc_co_u32_e64 v181, s[6:7], -1, v155, s[6:7]
	v_add_co_u32_e64 v182, s[6:7], s37, v154
	ds_read_b128 v[82:85], v190 offset:4128
	ds_read_b128 v[86:89], v190 offset:4144
	ds_read_b128 v[98:101], v190 offset:8224
	ds_read_b128 v[110:113], v190 offset:8240
	ds_read_b128 v[94:97], v190 offset:12320
	ds_read_b128 v[90:93], v190 offset:12336
	ds_read_b128 v[114:117], v190 offset:16416
	ds_read_b128 v[130:133], v190 offset:16432
	ds_read_b128 v[106:109], v190 offset:20512
	ds_read_b128 v[102:105], v190 offset:20528
	ds_read_b128 v[134:137], v190 offset:24608
	ds_read_b128 v[138:141], v190 offset:24624
	ds_read_b128 v[122:125], v190 offset:28704
	ds_read_b128 v[118:121], v190 offset:28720
	ds_read_b128 v[126:129], v190 offset:32800
	ds_read_b128 v[142:145], v190 offset:32816
	v_addc_co_u32_e64 v183, s[6:7], -1, v155, s[6:7]
	v_add_co_u32_e64 v184, s[6:7], s38, v154
	v_addc_co_u32_e32 v195, vcc, -1, v155, vcc
	s_nop 0
	v_addc_co_u32_e64 v185, s[6:7], -1, v155, s[6:7]
	v_add_co_u32_e64 v186, s[6:7], s39, v154
	v_add_co_u32_e32 v196, vcc, 0xfffb8000, v154
	s_nop 0
	v_addc_co_u32_e64 v187, s[6:7], -1, v155, s[6:7]
	global_load_dword v174, v[174:175], off nt
	s_nop 0
	global_load_dword v176, v[176:177], off nt
	s_nop 0
	global_load_dword v178, v[178:179], off nt
	s_nop 0
	global_load_dword v180, v[180:181], off nt
	s_nop 0
	global_load_dword v182, v[182:183], off nt
	s_nop 0
	global_load_dword v184, v[184:185], off nt
	s_nop 0
	global_load_dword v186, v[186:187], off nt
	v_addc_co_u32_e32 v197, vcc, -1, v155, vcc
	global_load_dword v164, v[164:165], off nt
	s_nop 0
	global_load_dword v192, v[192:193], off nt
	s_nop 0
	global_load_dword v194, v[194:195], off nt
	s_waitcnt lgkmcnt(14)
	v_mov_b32_e32 v198, v18
	v_mov_b32_e32 v18, v20
	v_mov_b32_e32 v20, v58
	v_mov_b32_e32 v58, v60
	v_mov_b32_e32 v60, v66
	v_mov_b32_e32 v66, v68
	v_mov_b32_e32 v68, v74
	v_mov_b32_e32 v74, v76
	global_load_dword v76, v[196:197], off nt
	s_nop 0
	global_load_dword v166, v[166:167], off nt
	s_nop 0
	global_load_dword v168, v[168:169], off nt
	s_nop 0
	global_load_dword v170, v[170:171], off nt
	s_nop 0
	global_load_dword v172, v[172:173], off nt
	v_mov_b32_e32 v197, v22
	v_mov_b32_e32 v22, v15
	v_mov_b32_e32 v15, v24
	v_mov_b32_e32 v24, v17
	v_mov_b32_e32 v17, v26
	v_mov_b32_e32 v26, v63
	v_mov_b32_e32 v63, v28
	v_mov_b32_e32 v28, v65
	v_mov_b32_e32 v65, v34
	v_mov_b32_e32 v34, v71
	v_mov_b32_e32 v71, v36
	v_mov_b32_e32 v36, v73
	v_mov_b32_e32 v73, v42
	v_mov_b32_e32 v42, v79
	v_mov_b32_e32 v79, v44
	v_mov_b32_e32 v44, v81
	v_mov_b32_e32 v81, v82
	v_mov_b32_e32 v82, v7
	v_mov_b32_e32 v7, v84
	v_mov_b32_e32 v84, v9
	s_waitcnt lgkmcnt(11)
	v_mov_b32_e32 v9, v94
	v_mov_b32_e32 v94, v99
	v_mov_b32_e32 v99, v96
	v_mov_b32_e32 v96, v101
	s_waitcnt lgkmcnt(7)
	v_mov_b32_e32 v101, v106
	v_mov_b32_e32 v106, v115
	v_mov_b32_e32 v115, v108
	v_mov_b32_e32 v108, v117
	s_waitcnt lgkmcnt(3)
	v_mov_b32_e32 v117, v122
	v_mov_b32_e32 v122, v135
	v_mov_b32_e32 v199, v10
	v_mov_b32_e32 v10, v19
	v_mov_b32_e32 v19, v12
	v_mov_b32_e32 v12, v21
	v_mov_b32_e32 v21, v30
	v_mov_b32_e32 v30, v59
	v_mov_b32_e32 v196, v14
	v_mov_b32_e32 v14, v16
	v_mov_b32_e32 v16, v62
	v_mov_b32_e32 v62, v64
	v_mov_b32_e32 v64, v70
	v_mov_b32_e32 v70, v72
	v_mov_b32_e32 v72, v78
	v_mov_b32_e32 v78, v80
	v_mov_b32_e32 v80, v6
	v_mov_b32_e32 v6, v8
	v_mov_b32_e32 v8, v98
	v_mov_b32_e32 v98, v100
	v_mov_b32_e32 v100, v114
	v_mov_b32_e32 v114, v116
	v_mov_b32_e32 v116, v134
	v_mov_b32_e32 v59, v32
	v_mov_b32_e32 v32, v61
	v_mov_b32_e32 v61, v38
	v_mov_b32_e32 v38, v67
	v_mov_b32_e32 v67, v40
	v_mov_b32_e32 v40, v69
	v_mov_b32_e32 v69, v46
	v_mov_b32_e32 v46, v75
	v_mov_b32_e32 v134, v136
	v_mov_b32_e32 v135, v124
	s_waitcnt vmcnt(13)
; #define LAS __attribute__((address_space(3)))
; __device__ __forceinline__ void ada_item(int it, const float* c, const float* cctx, const float* ada_w, const float* ada_b, float* mod, LAS float* sl) {
;     ...
;     for (int k = wid * 128; k < wid * 128 + 128; k += 4) {
;         const float w0 = W[(size_t)k * 6144], w1 = W[(size_t)(k + 1) * 6144], w2 = W[(size_t)(k + 2) * 6144], w3 = W[(size_t)(k + 3) * 6144];
; #pragma unroll
;         for (int j = 0; j < 9; ++j) { const f32x4 s = *(const LAS f32x4*)(sl + j * 1024 + k); acc[j] += s[0] * w0 + s[1] * w1 + s[2] * w2 + s[3] * w3; }
;     }
	v_pk_mul_f32 v[82:83], v[176:177], v[82:83] op_sel_hi:[0,1]
	v_pk_mul_f32 v[94:95], v[176:177], v[94:95] op_sel_hi:[0,1]
	v_pk_mul_f32 v[106:107], v[176:177], v[106:107] op_sel_hi:[0,1]
	v_pk_mul_f32 v[122:123], v[176:177], v[122:123] op_sel_hi:[0,1]
	v_pk_fma_f32 v[80:81], v[174:175], v[80:81], v[82:83] op_sel_hi:[0,1,1]
	v_pk_fma_f32 v[8:9], v[174:175], v[8:9], v[94:95] op_sel_hi:[0,1,1]
	v_pk_fma_f32 v[82:83], v[174:175], v[100:101], v[106:107] op_sel_hi:[0,1,1]
	v_pk_fma_f32 v[94:95], v[174:175], v[116:117], v[122:123] op_sel_hi:[0,1,1]
	v_mov_b32_e32 v175, v176
	s_waitcnt vmcnt(6)
	v_pk_mul_f32 v[10:11], v[192:193], v[10:11] op_sel_hi:[0,1]
	v_pk_mul_f32 v[30:31], v[192:193], v[30:31] op_sel_hi:[0,1]
	v_pk_mul_f32 v[38:39], v[192:193], v[38:39] op_sel_hi:[0,1]
	v_pk_mul_f32 v[46:47], v[192:193], v[46:47] op_sel_hi:[0,1]
	v_pk_fma_f32 v[6:7], v[178:179], v[6:7], v[80:81] op_sel_hi:[0,1,1]
	v_pk_fma_f32 v[80:81], v[178:179], v[114:115], v[82:83] op_sel_hi:[0,1,1]
	v_pk_fma_f32 v[82:83], v[178:179], v[134:135], v[94:95] op_sel_hi:[0,1,1]
	s_waitcnt lgkmcnt(1)
	v_pk_mul_f32 v[94:95], v[174:175], v[126:127]
	v_pk_fma_f32 v[10:11], v[164:165], v[198:199], v[10:11] op_sel_hi:[0,1,1]
	v_pk_fma_f32 v[20:21], v[164:165], v[20:21], v[30:31] op_sel_hi:[0,1,1]
	v_mov_b32_e32 v75, v48
	v_mov_b32_e32 v48, v77
	v_pk_fma_f32 v[30:31], v[164:165], v[60:61], v[38:39] op_sel_hi:[0,1,1]
	v_pk_fma_f32 v[38:39], v[164:165], v[68:69], v[46:47] op_sel_hi:[0,1,1]
	v_mov_b32_e32 v165, v192
	v_add_f32_e32 v77, v94, v95
	s_waitcnt vmcnt(5)
	v_pk_fma_f32 v[10:11], v[194:195], v[18:19], v[10:11] op_sel_hi:[0,1,1]
	v_pk_fma_f32 v[18:19], v[194:195], v[58:59], v[20:21] op_sel_hi:[0,1,1]
	s_waitcnt vmcnt(2)
	v_pk_mul_f32 v[22:23], v[168:169], v[22:23] op_sel_hi:[0,1]
	v_pk_mul_f32 v[26:27], v[168:169], v[26:27] op_sel_hi:[0,1]
	v_pk_mul_f32 v[34:35], v[168:169], v[34:35] op_sel_hi:[0,1]
	v_pk_mul_f32 v[42:43], v[168:169], v[42:43] op_sel_hi:[0,1]
	v_mov_b32_e32 v124, v137
	v_mov_b32_e32 v137, v86
	v_mov_b32_e32 v86, v3
	v_mov_b32_e32 v3, v88
	v_mov_b32_e32 v88, v5
	v_mov_b32_e32 v5, v90
	v_mov_b32_e32 v90, v111
	v_mov_b32_e32 v111, v92
	v_mov_b32_e32 v92, v113
	v_mov_b32_e32 v113, v102
	v_mov_b32_e32 v102, v131
	v_mov_b32_e32 v131, v104
	v_mov_b32_e32 v104, v133
	v_mov_b32_e32 v133, v118
	v_mov_b32_e32 v118, v139
	v_pk_fma_f32 v[20:21], v[194:195], v[66:67], v[30:31] op_sel_hi:[0,1,1]
	v_pk_fma_f32 v[30:31], v[194:195], v[74:75], v[38:39] op_sel_hi:[0,1,1]
	v_pk_mul_f32 v[38:39], v[164:165], v[50:51]
	v_mov_b32_e32 v195, v76
	v_pk_fma_f32 v[10:11], v[76:77], v[12:13], v[10:11] op_sel_hi:[0,1,1]
	v_pk_fma_f32 v[12:13], v[76:77], v[32:33], v[18:19] op_sel_hi:[0,1,1]
	v_pk_fma_f32 v[22:23], v[166:167], v[196:197], v[22:23] op_sel_hi:[0,1,1]
	v_pk_fma_f32 v[16:17], v[166:167], v[16:17], v[26:27] op_sel_hi:[0,1,1]
	v_pk_fma_f32 v[26:27], v[166:167], v[64:65], v[34:35] op_sel_hi:[0,1,1]
	v_pk_fma_f32 v[32:33], v[166:167], v[72:73], v[42:43] op_sel_hi:[0,1,1]
	v_mov_b32_e32 v167, v168
	v_mov_b32_e32 v136, v2
	v_mov_b32_e32 v2, v4
	v_mov_b32_e32 v4, v110
	v_mov_b32_e32 v110, v112
	v_mov_b32_e32 v112, v130
	v_mov_b32_e32 v130, v132
	v_mov_b32_e32 v132, v138
	v_pk_mul_f32 v[86:87], v[184:185], v[86:87] op_sel_hi:[0,1]
	v_pk_mul_f32 v[90:91], v[184:185], v[90:91] op_sel_hi:[0,1]
	v_pk_mul_f32 v[102:103], v[184:185], v[102:103] op_sel_hi:[0,1]
	v_pk_mul_f32 v[118:119], v[184:185], v[118:119] op_sel_hi:[0,1]
	v_pk_fma_f32 v[18:19], v[76:77], v[40:41], v[20:21] op_sel_hi:[0,1,1]
	v_pk_fma_f32 v[20:21], v[76:77], v[48:49], v[30:31] op_sel_hi:[0,1,1]
	v_pk_mul_f32 v[30:31], v[194:195], v[52:53]
	v_add_f32_e32 v38, v38, v39
	s_waitcnt vmcnt(1)
	v_pk_fma_f32 v[14:15], v[170:171], v[14:15], v[22:23] op_sel_hi:[0,1,1]
	v_pk_fma_f32 v[16:17], v[170:171], v[62:63], v[16:17] op_sel_hi:[0,1,1]
	v_pk_fma_f32 v[22:23], v[170:171], v[70:71], v[26:27] op_sel_hi:[0,1,1]
	v_pk_fma_f32 v[26:27], v[170:171], v[78:79], v[32:33] op_sel_hi:[0,1,1]
	v_pk_mul_f32 v[32:33], v[166:167], v[54:55]
	s_waitcnt vmcnt(0)
; #define LAS __attribute__((address_space(3)))
; __device__ __forceinline__ void ada_item(int it, const float* c, const float* cctx, const float* ada_w, const float* ada_b, float* mod, LAS float* sl) {
;     ...
;     for (int k = wid * 128; k < wid * 128 + 128; k += 4) {
;         const float w0 = W[(size_t)k * 6144], w1 = W[(size_t)(k + 1) * 6144], w2 = W[(size_t)(k + 2) * 6144], w3 = W[(size_t)(k + 3) * 6144];
; #pragma unroll
;         for (int j = 0; j < 9; ++j) { const f32x4 s = *(const LAS f32x4*)(sl + j * 1024 + k); acc[j] += s[0] * w0 + s[1] * w1 + s[2] * w2 + s[3] * w3; }
;     }
;     LAS float* red = sl + 9216;
; #pragma unroll
;     for (int j = 0; j < 9; ++j) red[(wid * 9 + j) * 64 + lane] = acc[j];
;     __syncthreads();
;     for (int o = tid; o < 576; o += 512) { const int j = o >> 6, l = o & 63; float s = 0.f;
; #pragma unroll
;         for (int w = 0; w < 8; ++w) s += red[(w * 9 + j) * 64 + l];
;         const int nn = cb * 64 + l; mod[((size_t)layer * 9 + j) * 6144 + nn] = s + ada_b[layer * 6144 + nn]; }
	v_mov_b32_e32 v171, v172
	v_mov_b32_e32 v138, v140
	v_mov_b32_e32 v139, v120
	v_pk_fma_f32 v[86:87], v[182:183], v[136:137], v[86:87] op_sel_hi:[0,1,1]
	v_pk_fma_f32 v[4:5], v[182:183], v[4:5], v[90:91] op_sel_hi:[0,1,1]
	v_pk_fma_f32 v[90:91], v[182:183], v[112:113], v[102:103] op_sel_hi:[0,1,1]
	v_pk_fma_f32 v[100:101], v[182:183], v[132:133], v[118:119] op_sel_hi:[0,1,1]
	v_mov_b32_e32 v183, v184
	v_pk_fma_f32 v[8:9], v[178:179], v[98:99], v[8:9] op_sel_hi:[0,1,1]
	v_mov_b32_e32 v179, v180
	v_pk_add_f32 v[10:11], v[156:157], v[10:11]
	v_pk_add_f32 v[18:19], v[160:161], v[18:19]
	v_add_f32_e32 v30, v30, v38
	v_pk_fma_f32 v[14:15], v[172:173], v[24:25], v[14:15] op_sel_hi:[0,1,1]
	v_pk_fma_f32 v[16:17], v[172:173], v[28:29], v[16:17] op_sel_hi:[0,1,1]
	v_pk_fma_f32 v[22:23], v[172:173], v[36:37], v[22:23] op_sel_hi:[0,1,1]
	v_pk_fma_f32 v[24:25], v[172:173], v[44:45], v[26:27] op_sel_hi:[0,1,1]
	v_pk_mul_f32 v[26:27], v[170:171], v[56:57]
	v_add_f32_e32 v28, v32, v33
	v_pk_fma_f32 v[2:3], v[186:187], v[2:3], v[86:87] op_sel_hi:[0,1,1]
	v_pk_fma_f32 v[4:5], v[186:187], v[110:111], v[4:5] op_sel_hi:[0,1,1]
	v_pk_fma_f32 v[86:87], v[186:187], v[130:131], v[90:91] op_sel_hi:[0,1,1]
	v_pk_fma_f32 v[90:91], v[186:187], v[138:139], v[100:101] op_sel_hi:[0,1,1]
	s_waitcnt lgkmcnt(0)
	v_pk_mul_f32 v[98:99], v[182:183], v[142:143]
	v_mov_b32_e32 v187, v148
	v_pk_mul_f32 v[68:69], v[178:179], v[128:129]
	v_add_f32_e32 v30, v31, v30
	v_pk_add_f32 v[10:11], v[10:11], v[14:15]
	v_pk_add_f32 v[14:15], v[18:19], v[22:23]
	v_add_f32_e32 v18, v26, v28
	v_pk_fma_f32 v[6:7], v[180:181], v[84:85], v[6:7] op_sel_hi:[0,1,1]
	v_pk_fma_f32 v[46:47], v[180:181], v[108:109], v[80:81] op_sel_hi:[0,1,1]
	v_pk_fma_f32 v[80:81], v[148:149], v[104:105], v[86:87] op_sel_hi:[0,1,1]
	v_pk_mul_f32 v[84:85], v[186:187], v[144:145]
	v_add_f32_e32 v86, v98, v99
	v_add_f32_e32 v50, v68, v77
	v_pk_add_f32 v[12:13], v[158:159], v[12:13]
	v_pk_add_f32 v[20:21], v[162:163], v[20:21]
	v_add_f32_e32 v29, v191, v30
	v_add_f32_e32 v18, v27, v18
	v_add_u32_e32 v189, 16, v189
	v_mov_b32_e32 v120, v141
	v_pk_fma_f32 v[8:9], v[180:181], v[96:97], v[8:9] op_sel_hi:[0,1,1]
	v_pk_fma_f32 v[60:61], v[180:181], v[124:125], v[82:83] op_sel_hi:[0,1,1]
	v_pk_fma_f32 v[2:3], v[148:149], v[88:89], v[2:3] op_sel_hi:[0,1,1]
	v_add_f32_e32 v51, v84, v86
	v_add_f32_e32 v34, v69, v50
	v_pk_add_f32 v[12:13], v[12:13], v[16:17]
	v_pk_add_f32 v[16:17], v[20:21], v[24:25]
	v_pk_add_f32 v[6:7], v[10:11], v[6:7]
	v_pk_add_f32 v[10:11], v[14:15], v[46:47]
	v_add_f32_e32 v14, v29, v18
	v_cmp_ge_i32_e64 s[6:7], v189, v188
	v_pk_fma_f32 v[4:5], v[148:149], v[92:93], v[4:5] op_sel_hi:[0,1,1]
	v_pk_fma_f32 v[82:83], v[148:149], v[120:121], v[90:91] op_sel_hi:[0,1,1]
	v_add_f32_e32 v35, v85, v51
	v_pk_add_f32 v[8:9], v[12:13], v[8:9]
	v_pk_add_f32 v[12:13], v[16:17], v[60:61]
	v_pk_add_f32 v[156:157], v[6:7], v[2:3]
	v_add_f32_e32 v2, v14, v34
	v_add_u32_e32 v190, 64, v190
	s_or_b64 s[2:3], s[6:7], s[2:3]
	v_lshl_add_u64 v[154:155], v[154:155], 0, s[16:17]
	v_pk_add_f32 v[158:159], v[8:9], v[4:5]
	v_pk_add_f32 v[160:161], v[10:11], v[80:81]
	v_pk_add_f32 v[162:163], v[12:13], v[82:83]
	v_add_f32_e32 v191, v2, v35
	s_andn2_b64 exec, exec, s[2:3]
	s_cbranch_execnz .LBB0_12
	s_or_b64 exec, exec, s[2:3]
	v_lshl_add_u32 v2, v151, 2, 0
	v_mad_u64_u32 v[4:5], s[2:3], v147, s40, v[2:3]
	v_cmp_gt_i32_e32 vcc, s41, v150
	ds_write2st64_b32 v4, v156, v157 offset0:144 offset1:145
	ds_write2st64_b32 v4, v158, v159 offset0:146 offset1:147
	ds_write2st64_b32 v4, v160, v161 offset0:148 offset1:149
	ds_write2st64_b32 v4, v162, v163 offset0:150 offset1:151
	ds_write_b32 v4, v191 offset:38912
	s_waitcnt lgkmcnt(0)
	s_barrier
	s_and_saveexec_b64 s[2:3], vcc
	s_cbranch_execz .LBB0_7
	s_mul_i32 s21, s20, 0x1800
	v_add_u32_e32 v4, s21, v152
	v_ashrrev_i32_e32 v5, 31, v4
	s_mul_hi_i32 s7, s20, 9
	s_mul_i32 s6, s20, 9
	v_lshl_add_u64 v[4:5], v[4:5], 2, s[12:13]
	v_lshl_add_u64 v[6:7], v[152:153], 2, s[54:55]
	s_mov_b64 s[20:21], 0

; __device__ __forceinline__ unsigned cvt_pk_bf16(float lo, float hi) { unsigned r; asm volatile("v_cvt_pk_bf16_f32 %0, %1, %2" : "=v"(r) : "v"(lo), "v"(hi)); return r; }
; #define LAS __attribute__((address_space(3)))
; __device__ __forceinline__ void transpose_item(const float* W, int K, int N, bf16_t* WT, LAS float* scr, int item, int lane) {
;     const int nblk = N / 32, kb = item / nblk, nb = item % nblk, k0 = 64 * kb, n0 = 32 * nb;
;     f32x4 tv[8];
; #pragma unroll
;     for (int i = 0; i < 8; ++i) tv[i] = *(const f32x4*)(W + (size_t)(k0 + 8 * i + (lane >> 3)) * N + n0 + 4 * (lane & 7));
; #pragma unroll
;     for (int i = 0; i < 8; ++i) { LAS float* d = scr + (8 * i + (lane >> 3)) * 33 + 4 * (lane & 7); d[0] = tv[i][0]; d[1] = tv[i][1]; d[2] = tv[i][2]; d[3] = tv[i][3]; }
;     __builtin_amdgcn_wave_barrier();
;     const int c = lane & 7;
; #pragma unroll
;     for (int j = 0; j < 4; ++j) { const int n = (lane >> 3) + 8 * j; const LAS float* s = scr + (8 * c) * 33 + n;
;         u32x4 o; o.x = cvt_pk_bf16(s[0 * 33], s[1 * 33]); o.y = cvt_pk_bf16(s[2 * 33], s[3 * 33]); o.z = cvt_pk_bf16(s[4 * 33], s[5 * 33]); o.w = cvt_pk_bf16(s[6 * 33], s[7 * 33]);
;         *(u32x4*)(WT + (size_t)(n0 + n) * K + k0 + 8 * c) = o; }
;     __builtin_amdgcn_wave_barrier();
; __global__ void __launch_bounds__(512, 2) mega_fwd(Args a) {
;     ...
;             { const int l = r / 1408; transpose_item(a.in[21] + (size_t)l * FFN * 1024, FFN, 1024, Wdn + (size_t)l * 1024 * FFN, scr, r % 1408, lane); } } }
.LBB0_19:
	v_cmp_lt_i32_e32 vcc, s39, v1
	s_and_saveexec_b64 s[2:3], vcc
	s_xor_b64 s[2:3], exec, s[2:3]
	s_cbranch_execz .LBB0_37
	v_cmp_lt_u32_e32 vcc, s40, v1
	s_and_saveexec_b64 s[6:7], vcc
	s_xor_b64 s[14:15], exec, s[6:7]
	s_cbranch_execz .LBB0_34
	v_cmp_lt_u32_e32 vcc, s41, v1
	s_and_saveexec_b64 s[6:7], vcc
	s_xor_b64 s[30:31], exec, s[6:7]
	s_cbranch_execz .LBB0_31
	v_cmp_lt_u32_e32 vcc, s42, v1
	s_and_saveexec_b64 s[6:7], vcc
	s_xor_b64 s[34:35], exec, s[6:7]
	s_cbranch_execz .LBB0_28
	v_cmp_lt_u32_e32 vcc, s43, v1
	s_and_saveexec_b64 s[6:7], vcc
	s_xor_b64 s[36:37], exec, s[6:7]
	s_cbranch_execz .LBB0_25
	v_add_u32_e32 v21, 0xffffd600, v1
	v_cmp_lt_u32_e32 vcc, s44, v21
	v_cmp_gt_u32_e64 s[6:7], s45, v21
	s_nop 0
	v_cndmask_b32_e32 v2, 0, v46, vcc
	v_lshl_add_u64 v[52:53], s[28:29], 0, v[2:3]
	v_add_u32_e32 v2, 0xffffd080, v1
	v_cndmask_b32_e64 v2, v2, v21, s[6:7]
	v_ashrrev_i16_e32 v21, 15, v2
	v_lshrrev_b16_e32 v21, 11, v21
	v_add_u16_e32 v21, v2, v21
	v_ashrrev_i16_e32 v23, 5, v21
	v_and_b32_e32 v21, 0xffffffe0, v21
	v_sub_u16_e32 v2, v2, v21
	v_lshlrev_b32_sdwa v84, v48, sext(v23) dst_sel:DWORD dst_unused:UNUSED_PAD src0_sel:DWORD src1_sel:WORD_0
	v_lshlrev_b32_sdwa v86, v49, sext(v2) dst_sel:DWORD dst_unused:UNUSED_PAD src0_sel:DWORD src1_sel:WORD_0
	v_or_b32_e32 v80, v84, v24
	v_ashrrev_i32_e32 v87, 31, v86
	v_or_b32_e32 v54, 8, v80
	v_or_b32_e32 v60, 16, v80
	v_or_b32_e32 v62, 24, v80
	v_or_b32_e32 v68, 32, v80
	v_or_b32_e32 v70, 40, v80
	v_lshl_add_u64 v[52:53], v[86:87], 2, v[52:53]
	v_mov_b32_e32 v21, v3
	v_ashrrev_i32_e32 v81, 31, v80
	v_ashrrev_i32_e32 v55, 31, v54
	v_ashrrev_i32_e32 v61, 31, v60
	v_ashrrev_i32_e32 v63, 31, v62
	v_ashrrev_i32_e32 v69, 31, v68
	v_ashrrev_i32_e32 v71, 31, v70
	v_lshl_add_u64 v[82:83], v[52:53], 0, v[20:21]
	v_lshlrev_b64 v[52:53], 12, v[80:81]
	v_lshlrev_b64 v[54:55], 12, v[54:55]
	v_lshlrev_b64 v[60:61], 12, v[60:61]
	v_lshlrev_b64 v[62:63], 12, v[62:63]
	v_lshlrev_b64 v[68:69], 12, v[68:69]
	v_lshlrev_b64 v[70:71], 12, v[70:71]
	v_lshl_add_u64 v[52:53], v[82:83], 0, v[52:53]
	v_lshl_add_u64 v[56:57], v[82:83], 0, v[54:55]
	v_lshl_add_u64 v[60:61], v[82:83], 0, v[60:61]
	v_lshl_add_u64 v[64:65], v[82:83], 0, v[62:63]
	v_lshl_add_u64 v[68:69], v[82:83], 0, v[68:69]
	v_lshl_add_u64 v[72:73], v[82:83], 0, v[70:71]
	global_load_dwordx4 v[52:55], v[52:53], off nt
	s_nop 0
	global_load_dwordx4 v[56:59], v[56:57], off nt
	s_nop 0
	global_load_dwordx4 v[60:63], v[60:61], off nt
	s_nop 0
	global_load_dwordx4 v[64:67], v[64:65], off nt
	s_nop 0
	global_load_dwordx4 v[68:71], v[68:69], off nt
	s_nop 0
	global_load_dwordx4 v[72:75], v[72:73], off nt
	v_or_b32_e32 v76, 48, v80
	v_ashrrev_i32_e32 v77, 31, v76
	v_lshlrev_b64 v[76:77], 12, v[76:77]
	v_or_b32_e32 v80, 56, v80
	v_lshl_add_u64 v[76:77], v[82:83], 0, v[76:77]
	v_ashrrev_i32_e32 v81, 31, v80
	global_load_dwordx4 v[76:79], v[76:77], off nt
	v_lshlrev_b64 v[80:81], 12, v[80:81]
	v_lshl_add_u64 v[80:81], v[82:83], 0, v[80:81]
	global_load_dwordx4 v[80:83], v[80:81], off nt
	v_cndmask_b32_e32 v2, 0, v47, vcc
	v_ashrrev_i32_e32 v85, 31, v84
	v_mov_b32_e32 v23, v3
	s_waitcnt vmcnt(7)
	ds_write2_b32 v31, v52, v53 offset1:1
	ds_write2_b32 v31, v54, v55 offset0:2 offset1:3
	s_waitcnt vmcnt(6)
	ds_write2_b32 v32, v56, v57 offset1:1
	ds_write2_b32 v33, v58, v59 offset1:1
	s_waitcnt vmcnt(5)
	ds_write2_b32 v34, v60, v61 offset1:1
	ds_write2_b32 v35, v62, v63 offset1:1
	s_waitcnt vmcnt(4)
	ds_write2_b32 v36, v64, v65 offset1:1
	ds_write2_b32 v37, v66, v67 offset1:1
	s_waitcnt vmcnt(3)
	ds_write2_b32 v38, v68, v69 offset1:1
	ds_write2_b32 v39, v70, v71 offset1:1
	s_waitcnt vmcnt(2)
	ds_write2_b32 v40, v72, v73 offset1:1
	ds_write2_b32 v41, v74, v75 offset1:1
	s_waitcnt vmcnt(1)
	ds_write2_b32 v42, v76, v77 offset1:1
	ds_write2_b32 v43, v78, v79 offset1:1
	s_waitcnt vmcnt(0)
	ds_write2_b32 v44, v80, v81 offset1:1
	ds_write2_b32 v45, v82, v83 offset1:1
	v_lshl_add_u64 v[56:57], s[46:47], 0, v[2:3]
	v_or_b32_e32 v2, v86, v24
	ds_read2_b32 v[52:53], v28 offset1:33
	v_lshl_add_u64 v[56:57], v[84:85], 1, v[56:57]
	v_mul_i32_i24_e32 v60, 0xb00, v2
	s_waitcnt lgkmcnt(0)
	v_cvt_pk_bf16_f32 v52, v52, v53
	ds_read2_b32 v[54:55], v28 offset0:66 offset1:99
	v_lshl_add_u64 v[56:57], v[56:57], 0, v[22:23]
	v_ashrrev_i32_e32 v61, 31, v60
	s_waitcnt lgkmcnt(0)
	v_cvt_pk_bf16_f32 v53, v54, v55
	ds_read2_b32 v[54:55], v28 offset0:132 offset1:165
	v_lshl_add_u64 v[60:61], v[60:61], 1, v[56:57]
	v_or_b32_e32 v2, v86, v25
	s_waitcnt lgkmcnt(0)
	v_cvt_pk_bf16_f32 v54, v54, v55
	ds_read2_b32 v[58:59], v28 offset0:198 offset1:231
	s_waitcnt lgkmcnt(0)
	v_cvt_pk_bf16_f32 v55, v58, v59
	global_store_dwordx4 v[60:61], v[52:55], off
	v_mul_i32_i24_e32 v60, 0xb00, v2
	ds_read2_b32 v[58:59], v28 offset0:8 offset1:41
	s_waitcnt lgkmcnt(0)
	v_cvt_pk_bf16_f32 v52, v58, v59
	ds_read2_b32 v[54:55], v28 offset0:74 offset1:107
	v_ashrrev_i32_e32 v61, 31, v60
	s_waitcnt lgkmcnt(0)
	v_cvt_pk_bf16_f32 v53, v54, v55
	ds_read2_b32 v[54:55], v28 offset0:140 offset1:173
	v_lshl_add_u64 v[60:61], v[60:61], 1, v[56:57]
	v_or_b32_e32 v2, v86, v26
	s_waitcnt lgkmcnt(0)
	v_cvt_pk_bf16_f32 v54, v54, v55
	ds_read2_b32 v[58:59], v28 offset0:206 offset1:239
	s_waitcnt lgkmcnt(0)
	v_cvt_pk_bf16_f32 v55, v58, v59
	global_store_dwordx4 v[60:61], v[52:55], off
	v_mul_i32_i24_e32 v60, 0xb00, v2
	ds_read2_b32 v[58:59], v28 offset0:16 offset1:49
	s_waitcnt lgkmcnt(0)
	v_cvt_pk_bf16_f32 v52, v58, v59
	ds_read2_b32 v[54:55], v28 offset0:82 offset1:115
	v_ashrrev_i32_e32 v61, 31, v60
	s_waitcnt lgkmcnt(0)
	v_cvt_pk_bf16_f32 v53, v54, v55
	ds_read2_b32 v[54:55], v28 offset0:148 offset1:181
	v_lshl_add_u64 v[60:61], v[60:61], 1, v[56:57]
	v_or_b32_e32 v2, v86, v27
	s_waitcnt lgkmcnt(0)
	v_cvt_pk_bf16_f32 v54, v54, v55
	ds_read2_b32 v[58:59], v28 offset0:214 offset1:247
	s_waitcnt lgkmcnt(0)
	v_cvt_pk_bf16_f32 v55, v58, v59
	global_store_dwordx4 v[60:61], v[52:55], off
	v_mul_i32_i24_e32 v60, 0xb00, v2
	ds_read2_b32 v[58:59], v28 offset0:24 offset1:57
	s_waitcnt lgkmcnt(0)
	v_cvt_pk_bf16_f32 v52, v58, v59
	ds_read2_b32 v[54:55], v28 offset0:90 offset1:123
	v_ashrrev_i32_e32 v61, 31, v60
	s_waitcnt lgkmcnt(0)
	v_cvt_pk_bf16_f32 v53, v54, v55
	ds_read2_b32 v[54:55], v28 offset0:156 offset1:189
	v_lshl_add_u64 v[56:57], v[60:61], 1, v[56:57]
	s_waitcnt lgkmcnt(0)
	v_cvt_pk_bf16_f32 v54, v54, v55
	ds_read2_b32 v[58:59], v28 offset0:222 offset1:255
	s_waitcnt lgkmcnt(0)
	v_cvt_pk_bf16_f32 v55, v58, v59
	global_store_dwordx4 v[56:57], v[52:55], off
; __device__ __forceinline__ unsigned cvt_pk_bf16(float lo, float hi) { unsigned r; asm volatile("v_cvt_pk_bf16_f32 %0, %1, %2" : "=v"(r) : "v"(lo), "v"(hi)); return r; }
; #define LAS __attribute__((address_space(3)))
; __device__ __forceinline__ void transpose_item(const float* W, int K, int N, bf16_t* WT, LAS float* scr, int item, int lane) {
;     const int nblk = N / 32, kb = item / nblk, nb = item % nblk, k0 = 64 * kb, n0 = 32 * nb;
;     f32x4 tv[8];
; #pragma unroll
;     for (int i = 0; i < 8; ++i) tv[i] = *(const f32x4*)(W + (size_t)(k0 + 8 * i + (lane >> 3)) * N + n0 + 4 * (lane & 7));
; #pragma unroll
;     for (int i = 0; i < 8; ++i) { LAS float* d = scr + (8 * i + (lane >> 3)) * 33 + 4 * (lane & 7); d[0] = tv[i][0]; d[1] = tv[i][1]; d[2] = tv[i][2]; d[3] = tv[i][3]; }
;     __builtin_amdgcn_wave_barrier();
;     const int c = lane & 7;
; #pragma unroll
;     for (int j = 0; j < 4; ++j) { const int n = (lane >> 3) + 8 * j; const LAS float* s = scr + (8 * c) * 33 + n;
;         u32x4 o; o.x = cvt_pk_bf16(s[0 * 33], s[1 * 33]); o.y = cvt_pk_bf16(s[2 * 33], s[3 * 33]); o.z = cvt_pk_bf16(s[4 * 33], s[5 * 33]); o.w = cvt_pk_bf16(s[6 * 33], s[7 * 33]);
;         *(u32x4*)(WT + (size_t)(n0 + n) * K + k0 + 8 * c) = o; }
;     __builtin_amdgcn_wave_barrier();
; __global__ void __launch_bounds__(512, 2) mega_fwd(Args a) {
;     ...
;             if (r < 5632) { const int l = r / 2816; transpose_item(a.in[18] + (size_t)l * 1024 * FFN2, 1024, FFN2, Wup + (size_t)l * FFN2 * 1024, scr, r % 2816, lane); continue; } r -= 5632;
.LBB0_25:
	s_andn2_saveexec_b64 s[36:37], s[36:37]
	s_cbranch_execz .LBB0_27
	v_add_u32_e32 v21, 0xffffec00, v1
	v_cmp_lt_u32_e32 vcc, s49, v21
	v_cmp_gt_u32_e64 s[6:7], s48, v21
	s_nop 0
	v_cndmask_b32_e32 v2, 0, v50, vcc
	v_lshl_add_u64 v[52:53], s[10:11], 0, v[2:3]
	v_add_u32_e32 v2, 0xffffe100, v1
	v_cndmask_b32_e64 v2, v2, v21, s[6:7]
	v_mul_i32_i24_sdwa v21, sext(v2), s56 dst_sel:DWORD dst_unused:UNUSED_PAD src0_sel:WORD_0 src1_sel:DWORD
	v_lshrrev_b32_e32 v23, 31, v21
	v_ashrrev_i32_e32 v21, 19, v21
	v_add_u16_e32 v21, v21, v23
	v_mul_lo_u16_e32 v23, 0xb0, v21
	v_sub_u16_e32 v2, v2, v23
	v_lshlrev_b32_sdwa v84, v48, sext(v21) dst_sel:DWORD dst_unused:UNUSED_PAD src0_sel:DWORD src1_sel:WORD_0
	v_lshlrev_b32_sdwa v86, v49, sext(v2) dst_sel:DWORD dst_unused:UNUSED_PAD src0_sel:DWORD src1_sel:WORD_0
	v_or_b32_e32 v2, v84, v24
	v_ashrrev_i32_e32 v87, 31, v86
	v_lshl_add_u64 v[52:53], v[86:87], 2, v[52:53]
	v_mov_b32_e32 v21, v3
	v_mul_i32_i24_e32 v54, 0x5800, v2
	v_lshl_add_u64 v[52:53], v[52:53], 0, v[20:21]
	v_ashrrev_i32_e32 v55, 31, v54
	v_lshl_add_u64 v[80:81], v[52:53], 0, v[54:55]
	v_add_co_u32_e64 v56, s[6:7], s57, v80
	v_cndmask_b32_e32 v2, 0, v46, vcc
	s_nop 0
	v_addc_co_u32_e64 v57, s[6:7], 0, v81, s[6:7]
	v_add_co_u32_e64 v60, s[6:7], s58, v80
	global_load_dwordx4 v[52:55], v[80:81], off nt
	s_nop 0
	global_load_dwordx4 v[56:59], v[56:57], off nt
	v_addc_co_u32_e64 v61, s[6:7], 0, v81, s[6:7]
	v_add_co_u32_e64 v64, s[6:7], s59, v80
	v_ashrrev_i32_e32 v85, 31, v84
	s_nop 0
	v_addc_co_u32_e64 v65, s[6:7], 0, v81, s[6:7]
	v_add_co_u32_e64 v68, s[6:7], s60, v80
	global_load_dwordx4 v[60:63], v[60:61], off nt
	s_nop 0
	global_load_dwordx4 v[64:67], v[64:65], off nt
	v_addc_co_u32_e64 v69, s[6:7], 0, v81, s[6:7]
	v_add_co_u32_e64 v72, s[6:7], s61, v80
	v_mov_b32_e32 v23, v3
	s_nop 0
	v_addc_co_u32_e64 v73, s[6:7], 0, v81, s[6:7]
	global_load_dwordx4 v[68:71], v[68:69], off nt
	s_nop 0
	global_load_dwordx4 v[72:75], v[72:73], off nt
	v_add_co_u32_e64 v76, s[6:7], s62, v80
	s_nop 1
	v_addc_co_u32_e64 v77, s[6:7], 0, v81, s[6:7]
	global_load_dwordx4 v[76:79], v[76:77], off nt
	v_add_co_u32_e64 v80, s[6:7], s63, v80
	s_nop 1
	v_addc_co_u32_e64 v81, s[6:7], 0, v81, s[6:7]
	global_load_dwordx4 v[80:83], v[80:81], off nt
	s_waitcnt vmcnt(7)
	ds_write2_b32 v31, v52, v53 offset1:1
	ds_write2_b32 v31, v54, v55 offset0:2 offset1:3
	s_waitcnt vmcnt(6)
	ds_write2_b32 v32, v56, v57 offset1:1
	ds_write2_b32 v33, v58, v59 offset1:1
	s_waitcnt vmcnt(5)
	ds_write2_b32 v34, v60, v61 offset1:1
	ds_write2_b32 v35, v62, v63 offset1:1
	s_waitcnt vmcnt(4)
	ds_write2_b32 v36, v64, v65 offset1:1
	ds_write2_b32 v37, v66, v67 offset1:1
	s_waitcnt vmcnt(3)
	ds_write2_b32 v38, v68, v69 offset1:1
	ds_write2_b32 v39, v70, v71 offset1:1
	s_waitcnt vmcnt(2)
	ds_write2_b32 v40, v72, v73 offset1:1
	ds_write2_b32 v41, v74, v75 offset1:1
	s_waitcnt vmcnt(1)
	ds_write2_b32 v42, v76, v77 offset1:1
	ds_write2_b32 v43, v78, v79 offset1:1
	s_waitcnt vmcnt(0)
	ds_write2_b32 v44, v80, v81 offset1:1
	ds_write2_b32 v45, v82, v83 offset1:1
	v_lshl_add_u64 v[56:57], s[16:17], 0, v[2:3]
	v_or_b32_e32 v60, v86, v24
	ds_read2_b32 v[52:53], v28 offset1:33
	v_lshl_add_u64 v[56:57], v[84:85], 1, v[56:57]
	v_ashrrev_i32_e32 v61, 31, v60
	s_waitcnt lgkmcnt(0)
	v_cvt_pk_bf16_f32 v52, v52, v53
	ds_read2_b32 v[54:55], v28 offset0:66 offset1:99
	v_lshl_add_u64 v[56:57], v[56:57], 0, v[22:23]
	v_lshlrev_b64 v[60:61], 11, v[60:61]
	s_waitcnt lgkmcnt(0)
	v_cvt_pk_bf16_f32 v53, v54, v55
	ds_read2_b32 v[54:55], v28 offset0:132 offset1:165
	v_lshl_add_u64 v[60:61], v[56:57], 0, v[60:61]
	s_waitcnt lgkmcnt(0)
	v_cvt_pk_bf16_f32 v54, v54, v55
	ds_read2_b32 v[58:59], v28 offset0:198 offset1:231
	s_waitcnt lgkmcnt(0)
	v_cvt_pk_bf16_f32 v55, v58, v59
	global_store_dwordx4 v[60:61], v[52:55], off
	v_or_b32_e32 v60, v86, v25
	v_ashrrev_i32_e32 v61, 31, v60
	ds_read2_b32 v[58:59], v28 offset0:8 offset1:41
	s_waitcnt lgkmcnt(0)
	v_cvt_pk_bf16_f32 v52, v58, v59
	ds_read2_b32 v[54:55], v28 offset0:74 offset1:107
	v_lshlrev_b64 v[60:61], 11, v[60:61]
	s_waitcnt lgkmcnt(0)
	v_cvt_pk_bf16_f32 v53, v54, v55
	ds_read2_b32 v[54:55], v28 offset0:140 offset1:173
	v_lshl_add_u64 v[60:61], v[56:57], 0, v[60:61]
	s_waitcnt lgkmcnt(0)
	v_cvt_pk_bf16_f32 v54, v54, v55
	ds_read2_b32 v[58:59], v28 offset0:206 offset1:239
	s_waitcnt lgkmcnt(0)
	v_cvt_pk_bf16_f32 v55, v58, v59
	global_store_dwordx4 v[60:61], v[52:55], off
	v_or_b32_e32 v60, v86, v26
	v_ashrrev_i32_e32 v61, 31, v60
	ds_read2_b32 v[58:59], v28 offset0:16 offset1:49
	s_waitcnt lgkmcnt(0)
	v_cvt_pk_bf16_f32 v52, v58, v59
	ds_read2_b32 v[54:55], v28 offset0:82 offset1:115
	v_lshlrev_b64 v[60:61], 11, v[60:61]
	s_waitcnt lgkmcnt(0)
	v_cvt_pk_bf16_f32 v53, v54, v55
	ds_read2_b32 v[54:55], v28 offset0:148 offset1:181
	v_lshl_add_u64 v[60:61], v[56:57], 0, v[60:61]
	s_waitcnt lgkmcnt(0)
	v_cvt_pk_bf16_f32 v54, v54, v55
	ds_read2_b32 v[58:59], v28 offset0:214 offset1:247
	s_waitcnt lgkmcnt(0)
	v_cvt_pk_bf16_f32 v55, v58, v59
	global_store_dwordx4 v[60:61], v[52:55], off
	v_or_b32_e32 v60, v86, v27
	v_ashrrev_i32_e32 v61, 31, v60
	ds_read2_b32 v[58:59], v28 offset0:24 offset1:57
	s_waitcnt lgkmcnt(0)
	v_cvt_pk_bf16_f32 v52, v58, v59
	ds_read2_b32 v[54:55], v28 offset0:90 offset1:123
	v_lshlrev_b64 v[60:61], 11, v[60:61]
	s_waitcnt lgkmcnt(0)
	v_cvt_pk_bf16_f32 v53, v54, v55
	ds_read2_b32 v[54:55], v28 offset0:156 offset1:189
	v_lshl_add_u64 v[56:57], v[56:57], 0, v[60:61]
	s_waitcnt lgkmcnt(0)
	v_cvt_pk_bf16_f32 v54, v54, v55
	ds_read2_b32 v[58:59], v28 offset0:222 offset1:255
	s_waitcnt lgkmcnt(0)
	v_cvt_pk_bf16_f32 v55, v58, v59
	global_store_dwordx4 v[56:57], v[52:55], off

; __device__ __forceinline__ unsigned cvt_pk_bf16(float lo, float hi) { unsigned r; asm volatile("v_cvt_pk_bf16_f32 %0, %1, %2" : "=v"(r) : "v"(lo), "v"(hi)); return r; }
; #define LAS __attribute__((address_space(3)))
; __device__ __forceinline__ void transpose_item(const float* W, int K, int N, bf16_t* WT, LAS float* scr, int item, int lane) {
;     const int nblk = N / 32, kb = item / nblk, nb = item % nblk, k0 = 64 * kb, n0 = 32 * nb;
;     f32x4 tv[8];
; #pragma unroll
;     for (int i = 0; i < 8; ++i) tv[i] = *(const f32x4*)(W + (size_t)(k0 + 8 * i + (lane >> 3)) * N + n0 + 4 * (lane & 7));
; #pragma unroll
;     for (int i = 0; i < 8; ++i) { LAS float* d = scr + (8 * i + (lane >> 3)) * 33 + 4 * (lane & 7); d[0] = tv[i][0]; d[1] = tv[i][1]; d[2] = tv[i][2]; d[3] = tv[i][3]; }
;     __builtin_amdgcn_wave_barrier();
;     const int c = lane & 7;
; #pragma unroll
;     for (int j = 0; j < 4; ++j) { const int n = (lane >> 3) + 8 * j; const LAS float* s = scr + (8 * c) * 33 + n;
;         u32x4 o; o.x = cvt_pk_bf16(s[0 * 33], s[1 * 33]); o.y = cvt_pk_bf16(s[2 * 33], s[3 * 33]); o.z = cvt_pk_bf16(s[4 * 33], s[5 * 33]); o.w = cvt_pk_bf16(s[6 * 33], s[7 * 33]);
;         *(u32x4*)(WT + (size_t)(n0 + n) * K + k0 + 8 * c) = o; }
;     __builtin_amdgcn_wave_barrier();
; __global__ void __launch_bounds__(512, 2) mega_fwd(Args a) {
;     ...
;             if (r < 512) { transpose_item(a.in[17], 1024, 1024, Wdo, scr, r, lane); continue; } r -= 512;
.LBB0_28:
	s_andn2_saveexec_b64 s[6:7], s[34:35]
	s_cbranch_execz .LBB0_30
	v_and_b32_e32 v21, 0x1ffc0, v30
	v_and_b32_e32 v23, 0x3e0, v29
	v_or_b32_e32 v51, v21, v24
	v_lshlrev_b32_e32 v2, 2, v23
	v_lshl_add_u64 v[52:53], v[4:5], 0, v[2:3]
	v_lshlrev_b32_e32 v2, 12, v51
	v_lshl_add_u64 v[80:81], v[52:53], 0, v[2:3]
	v_add_co_u32_e32 v56, vcc, 0x8000, v80
	v_or_b32_e32 v51, v23, v24
	s_nop 0
	v_addc_co_u32_e32 v57, vcc, 0, v81, vcc
	v_add_co_u32_e32 v60, vcc, 0x10000, v80
	global_load_dwordx4 v[52:55], v[80:81], off nt
	s_nop 0
	global_load_dwordx4 v[56:59], v[56:57], off nt
	v_addc_co_u32_e32 v61, vcc, 0, v81, vcc
	v_add_co_u32_e32 v64, vcc, 0x18000, v80
	v_lshlrev_b32_e32 v2, 1, v21
	s_nop 0
	v_addc_co_u32_e32 v65, vcc, 0, v81, vcc
	v_add_co_u32_e32 v68, vcc, 0x20000, v80
	global_load_dwordx4 v[60:63], v[60:61], off nt
	s_nop 0
	global_load_dwordx4 v[64:67], v[64:65], off nt
	v_addc_co_u32_e32 v69, vcc, 0, v81, vcc
	v_add_co_u32_e32 v72, vcc, 0x28000, v80
	s_nop 1
	v_addc_co_u32_e32 v73, vcc, 0, v81, vcc
	global_load_dwordx4 v[68:71], v[68:69], off nt
	s_nop 0
	global_load_dwordx4 v[72:75], v[72:73], off nt
	v_add_co_u32_e32 v76, vcc, 0x30000, v80
	s_nop 1
	v_addc_co_u32_e32 v77, vcc, 0, v81, vcc
	global_load_dwordx4 v[76:79], v[76:77], off nt
	v_add_co_u32_e32 v80, vcc, 0x38000, v80
	s_nop 1
	v_addc_co_u32_e32 v81, vcc, 0, v81, vcc
	global_load_dwordx4 v[80:83], v[80:81], off nt
	s_waitcnt vmcnt(7)
	ds_write2_b32 v31, v52, v53 offset1:1
	ds_write2_b32 v31, v54, v55 offset0:2 offset1:3
	s_waitcnt vmcnt(6)
	ds_write2_b32 v32, v56, v57 offset1:1
	ds_write2_b32 v33, v58, v59 offset1:1
	s_waitcnt vmcnt(5)
	ds_write2_b32 v34, v60, v61 offset1:1
	ds_write2_b32 v35, v62, v63 offset1:1
	s_waitcnt vmcnt(4)
	ds_write2_b32 v36, v64, v65 offset1:1
	ds_write2_b32 v37, v66, v67 offset1:1
	s_waitcnt vmcnt(3)
	ds_write2_b32 v38, v68, v69 offset1:1
	ds_write2_b32 v39, v70, v71 offset1:1
	s_waitcnt vmcnt(2)
	ds_write2_b32 v40, v72, v73 offset1:1
	ds_write2_b32 v41, v74, v75 offset1:1
	s_waitcnt vmcnt(1)
	ds_write2_b32 v42, v76, v77 offset1:1
	ds_write2_b32 v43, v78, v79 offset1:1
	s_waitcnt vmcnt(0)
	ds_write2_b32 v44, v80, v81 offset1:1
	ds_write2_b32 v45, v82, v83 offset1:1
	ds_read2_b32 v[52:53], v28 offset1:33
	s_waitcnt lgkmcnt(0)
	v_cvt_pk_bf16_f32 v52, v52, v53
	ds_read2_b32 v[54:55], v28 offset0:66 offset1:99
	s_waitcnt lgkmcnt(0)
	v_cvt_pk_bf16_f32 v53, v54, v55
	ds_read2_b32 v[54:55], v28 offset0:132 offset1:165
	v_lshl_add_u64 v[58:59], v[6:7], 0, v[2:3]
	v_lshlrev_b32_e32 v2, 11, v51
	s_waitcnt lgkmcnt(0)
	v_cvt_pk_bf16_f32 v54, v54, v55
	ds_read2_b32 v[56:57], v28 offset0:198 offset1:231
	s_waitcnt lgkmcnt(0)
	v_cvt_pk_bf16_f32 v55, v56, v57
	v_lshl_add_u64 v[60:61], v[58:59], 0, v[2:3]
	ds_read2_b32 v[56:57], v28 offset0:8 offset1:41
	global_store_dwordx4 v[60:61], v[52:55], off
	v_or_b32_e32 v2, v23, v25
	v_lshlrev_b32_e32 v2, 11, v2
	s_waitcnt lgkmcnt(0)
	v_cvt_pk_bf16_f32 v52, v56, v57
	ds_read2_b32 v[54:55], v28 offset0:74 offset1:107
	s_waitcnt lgkmcnt(0)
	v_cvt_pk_bf16_f32 v53, v54, v55
	ds_read2_b32 v[54:55], v28 offset0:140 offset1:173
	s_waitcnt lgkmcnt(0)
	v_cvt_pk_bf16_f32 v54, v54, v55
	ds_read2_b32 v[56:57], v28 offset0:206 offset1:239
	s_waitcnt lgkmcnt(0)
	v_cvt_pk_bf16_f32 v55, v56, v57
	v_lshl_add_u64 v[60:61], v[58:59], 0, v[2:3]
	ds_read2_b32 v[56:57], v28 offset0:16 offset1:49
	global_store_dwordx4 v[60:61], v[52:55], off
	v_or_b32_e32 v2, v23, v26
	v_lshlrev_b32_e32 v2, 11, v2
	s_waitcnt lgkmcnt(0)
	v_cvt_pk_bf16_f32 v52, v56, v57
	ds_read2_b32 v[54:55], v28 offset0:82 offset1:115
	s_waitcnt lgkmcnt(0)
	v_cvt_pk_bf16_f32 v53, v54, v55
	ds_read2_b32 v[54:55], v28 offset0:148 offset1:181
	s_waitcnt lgkmcnt(0)
	v_cvt_pk_bf16_f32 v54, v54, v55
	ds_read2_b32 v[56:57], v28 offset0:214 offset1:247
	s_waitcnt lgkmcnt(0)
	v_cvt_pk_bf16_f32 v55, v56, v57
	v_lshl_add_u64 v[60:61], v[58:59], 0, v[2:3]
	ds_read2_b32 v[56:57], v28 offset0:24 offset1:57
	global_store_dwordx4 v[60:61], v[52:55], off
	v_or_b32_e32 v2, v23, v27
	v_lshlrev_b32_e32 v2, 11, v2
	s_waitcnt lgkmcnt(0)
	v_cvt_pk_bf16_f32 v52, v56, v57
	ds_read2_b32 v[54:55], v28 offset0:90 offset1:123
	s_waitcnt lgkmcnt(0)
	v_cvt_pk_bf16_f32 v53, v54, v55
	ds_read2_b32 v[54:55], v28 offset0:156 offset1:189
	s_waitcnt lgkmcnt(0)
	v_cvt_pk_bf16_f32 v54, v54, v55
	ds_read2_b32 v[56:57], v28 offset0:222 offset1:255
	s_waitcnt lgkmcnt(0)
	v_cvt_pk_bf16_f32 v55, v56, v57
	v_lshl_add_u64 v[56:57], v[58:59], 0, v[2:3]
	global_store_dwordx4 v[56:57], v[52:55], off

; __device__ __forceinline__ unsigned cvt_pk_bf16(float lo, float hi) { unsigned r; asm volatile("v_cvt_pk_bf16_f32 %0, %1, %2" : "=v"(r) : "v"(lo), "v"(hi)); return r; }
; #define LAS __attribute__((address_space(3)))
; __device__ __forceinline__ void transpose_item(const float* W, int K, int N, bf16_t* WT, LAS float* scr, int item, int lane) {
;     const int nblk = N / 32, kb = item / nblk, nb = item % nblk, k0 = 64 * kb, n0 = 32 * nb;
;     f32x4 tv[8];
; #pragma unroll
;     for (int i = 0; i < 8; ++i) tv[i] = *(const f32x4*)(W + (size_t)(k0 + 8 * i + (lane >> 3)) * N + n0 + 4 * (lane & 7));
; #pragma unroll
;     for (int i = 0; i < 8; ++i) { LAS float* d = scr + (8 * i + (lane >> 3)) * 33 + 4 * (lane & 7); d[0] = tv[i][0]; d[1] = tv[i][1]; d[2] = tv[i][2]; d[3] = tv[i][3]; }
;     __builtin_amdgcn_wave_barrier();
;     const int c = lane & 7;
; #pragma unroll
;     for (int j = 0; j < 4; ++j) { const int n = (lane >> 3) + 8 * j; const LAS float* s = scr + (8 * c) * 33 + n;
;         u32x4 o; o.x = cvt_pk_bf16(s[0 * 33], s[1 * 33]); o.y = cvt_pk_bf16(s[2 * 33], s[3 * 33]); o.z = cvt_pk_bf16(s[4 * 33], s[5 * 33]); o.w = cvt_pk_bf16(s[6 * 33], s[7 * 33]);
;         *(u32x4*)(WT + (size_t)(n0 + n) * K + k0 + 8 * c) = o; }
;     __builtin_amdgcn_wave_barrier();
; __global__ void __launch_bounds__(512, 2) mega_fwd(Args a) {
;     ...
;             if (r < 1536) { transpose_item(a.in[11], 1024, 3072, Wqkv, scr, r, lane); continue; } r -= 1536;
.LBB0_31:
	s_andn2_saveexec_b64 s[6:7], s[30:31]
	s_cbranch_execz .LBB0_33
	v_add_u16_e32 v2, 0xf400, v1
	v_mul_u32_u24_e32 v21, 0xaaab, v2
	v_lshrrev_b32_e32 v23, 22, v21
	v_mul_lo_u16_e32 v23, 0x60, v23
	v_sub_u16_e32 v2, v2, v23
	v_and_b32_sdwa v21, v21, s66 dst_sel:DWORD dst_unused:UNUSED_PAD src0_sel:WORD_1 src1_sel:DWORD
	v_lshlrev_b16_e32 v23, 5, v2
	v_or_b32_e32 v51, v24, v21
	v_lshlrev_b32_e32 v2, 2, v23
	v_lshl_add_u64 v[52:53], v[8:9], 0, v[2:3]
	v_mul_u32_u24_e32 v2, 0xc00, v51
	v_lshlrev_b32_e32 v2, 2, v2
	v_lshl_add_u64 v[80:81], v[52:53], 0, v[2:3]
	v_add_co_u32_e32 v56, vcc, s64, v80
	v_or_b32_e32 v51, v24, v23
	s_nop 0
	v_addc_co_u32_e32 v57, vcc, 0, v81, vcc
	v_add_co_u32_e32 v60, vcc, s65, v80
	global_load_dwordx4 v[52:55], v[80:81], off nt
	s_nop 0
	global_load_dwordx4 v[56:59], v[56:57], off nt
	v_addc_co_u32_e32 v61, vcc, 0, v81, vcc
	v_add_co_u32_e32 v64, vcc, s67, v80
	v_lshlrev_b32_e32 v2, 1, v21
	s_nop 0
	v_addc_co_u32_e32 v65, vcc, 0, v81, vcc
	v_add_co_u32_e32 v68, vcc, s68, v80
	global_load_dwordx4 v[60:63], v[60:61], off nt
	s_nop 0
	global_load_dwordx4 v[64:67], v[64:65], off nt
	v_addc_co_u32_e32 v69, vcc, 0, v81, vcc
	v_add_co_u32_e32 v72, vcc, s69, v80
	s_nop 1
	v_addc_co_u32_e32 v73, vcc, 0, v81, vcc
	global_load_dwordx4 v[68:71], v[68:69], off nt
	s_nop 0
	global_load_dwordx4 v[72:75], v[72:73], off nt
	v_add_co_u32_e32 v76, vcc, s70, v80
	s_nop 1
	v_addc_co_u32_e32 v77, vcc, 0, v81, vcc
	global_load_dwordx4 v[76:79], v[76:77], off nt
	v_add_co_u32_e32 v80, vcc, s71, v80
	s_nop 1
	v_addc_co_u32_e32 v81, vcc, 0, v81, vcc
	global_load_dwordx4 v[80:83], v[80:81], off nt
	s_waitcnt vmcnt(7)
	ds_write2_b32 v31, v52, v53 offset1:1
	ds_write2_b32 v31, v54, v55 offset0:2 offset1:3
	s_waitcnt vmcnt(6)
	ds_write2_b32 v32, v56, v57 offset1:1
	ds_write2_b32 v33, v58, v59 offset1:1
	s_waitcnt vmcnt(5)
	ds_write2_b32 v34, v60, v61 offset1:1
	ds_write2_b32 v35, v62, v63 offset1:1
	s_waitcnt vmcnt(4)
	ds_write2_b32 v36, v64, v65 offset1:1
	ds_write2_b32 v37, v66, v67 offset1:1
	s_waitcnt vmcnt(3)
	ds_write2_b32 v38, v68, v69 offset1:1
	ds_write2_b32 v39, v70, v71 offset1:1
	s_waitcnt vmcnt(2)
	ds_write2_b32 v40, v72, v73 offset1:1
	ds_write2_b32 v41, v74, v75 offset1:1
	s_waitcnt vmcnt(1)
	ds_write2_b32 v42, v76, v77 offset1:1
	ds_write2_b32 v43, v78, v79 offset1:1
	s_waitcnt vmcnt(0)
	ds_write2_b32 v44, v80, v81 offset1:1
	ds_write2_b32 v45, v82, v83 offset1:1
	ds_read2_b32 v[52:53], v28 offset1:33
	s_waitcnt lgkmcnt(0)
	v_cvt_pk_bf16_f32 v52, v52, v53
	ds_read2_b32 v[54:55], v28 offset0:66 offset1:99
	s_waitcnt lgkmcnt(0)
	v_cvt_pk_bf16_f32 v53, v54, v55
	ds_read2_b32 v[54:55], v28 offset0:132 offset1:165
	v_lshl_add_u64 v[58:59], v[10:11], 0, v[2:3]
	v_lshlrev_b32_e32 v2, 11, v51
	s_waitcnt lgkmcnt(0)
	v_cvt_pk_bf16_f32 v54, v54, v55
	ds_read2_b32 v[56:57], v28 offset0:198 offset1:231
	s_waitcnt lgkmcnt(0)
	v_cvt_pk_bf16_f32 v55, v56, v57
	v_lshl_add_u64 v[60:61], v[58:59], 0, v[2:3]
	ds_read2_b32 v[56:57], v28 offset0:8 offset1:41
	global_store_dwordx4 v[60:61], v[52:55], off
	v_or_b32_e32 v2, v25, v23
	v_lshlrev_b32_e32 v2, 11, v2
	s_waitcnt lgkmcnt(0)
	v_cvt_pk_bf16_f32 v52, v56, v57
	ds_read2_b32 v[54:55], v28 offset0:74 offset1:107
	s_waitcnt lgkmcnt(0)
	v_cvt_pk_bf16_f32 v53, v54, v55
	ds_read2_b32 v[54:55], v28 offset0:140 offset1:173
	s_waitcnt lgkmcnt(0)
	v_cvt_pk_bf16_f32 v54, v54, v55
	ds_read2_b32 v[56:57], v28 offset0:206 offset1:239
	s_waitcnt lgkmcnt(0)
	v_cvt_pk_bf16_f32 v55, v56, v57
	v_lshl_add_u64 v[60:61], v[58:59], 0, v[2:3]
	ds_read2_b32 v[56:57], v28 offset0:16 offset1:49
	global_store_dwordx4 v[60:61], v[52:55], off
	v_or_b32_e32 v2, v26, v23
	v_lshlrev_b32_e32 v2, 11, v2
	s_waitcnt lgkmcnt(0)
	v_cvt_pk_bf16_f32 v52, v56, v57
	ds_read2_b32 v[54:55], v28 offset0:82 offset1:115
	s_waitcnt lgkmcnt(0)
	v_cvt_pk_bf16_f32 v53, v54, v55
	ds_read2_b32 v[54:55], v28 offset0:148 offset1:181
	s_waitcnt lgkmcnt(0)
	v_cvt_pk_bf16_f32 v54, v54, v55
	ds_read2_b32 v[56:57], v28 offset0:214 offset1:247
	s_waitcnt lgkmcnt(0)
	v_cvt_pk_bf16_f32 v55, v56, v57
	v_lshl_add_u64 v[60:61], v[58:59], 0, v[2:3]
	ds_read2_b32 v[56:57], v28 offset0:24 offset1:57
	global_store_dwordx4 v[60:61], v[52:55], off
	v_or_b32_e32 v2, v27, v23
	v_lshlrev_b32_e32 v2, 11, v2
	s_waitcnt lgkmcnt(0)
	v_cvt_pk_bf16_f32 v52, v56, v57
	ds_read2_b32 v[54:55], v28 offset0:90 offset1:123
	s_waitcnt lgkmcnt(0)
	v_cvt_pk_bf16_f32 v53, v54, v55
	ds_read2_b32 v[54:55], v28 offset0:156 offset1:189
	s_waitcnt lgkmcnt(0)
	v_cvt_pk_bf16_f32 v54, v54, v55
	ds_read2_b32 v[56:57], v28 offset0:222 offset1:255
	s_waitcnt lgkmcnt(0)
	v_cvt_pk_bf16_f32 v55, v56, v57
	v_lshl_add_u64 v[56:57], v[58:59], 0, v[2:3]
	global_store_dwordx4 v[56:57], v[52:55], off

; __device__ __forceinline__ unsigned cvt_pk_bf16(float lo, float hi) { unsigned r; asm volatile("v_cvt_pk_bf16_f32 %0, %1, %2" : "=v"(r) : "v"(lo), "v"(hi)); return r; }
; #define LAS __attribute__((address_space(3)))
; __device__ __forceinline__ void transpose_item(const float* W, int K, int N, bf16_t* WT, LAS float* scr, int item, int lane) {
;     const int nblk = N / 32, kb = item / nblk, nb = item % nblk, k0 = 64 * kb, n0 = 32 * nb;
;     f32x4 tv[8];
; #pragma unroll
;     for (int i = 0; i < 8; ++i) tv[i] = *(const f32x4*)(W + (size_t)(k0 + 8 * i + (lane >> 3)) * N + n0 + 4 * (lane & 7));
; #pragma unroll
;     for (int i = 0; i < 8; ++i) { LAS float* d = scr + (8 * i + (lane >> 3)) * 33 + 4 * (lane & 7); d[0] = tv[i][0]; d[1] = tv[i][1]; d[2] = tv[i][2]; d[3] = tv[i][3]; }
;     __builtin_amdgcn_wave_barrier();
;     const int c = lane & 7;
; #pragma unroll
;     for (int j = 0; j < 4; ++j) { const int n = (lane >> 3) + 8 * j; const LAS float* s = scr + (8 * c) * 33 + n;
;         u32x4 o; o.x = cvt_pk_bf16(s[0 * 33], s[1 * 33]); o.y = cvt_pk_bf16(s[2 * 33], s[3 * 33]); o.z = cvt_pk_bf16(s[4 * 33], s[5 * 33]); o.w = cvt_pk_bf16(s[6 * 33], s[7 * 33]);
;         *(u32x4*)(WT + (size_t)(n0 + n) * K + k0 + 8 * c) = o; }
;     __builtin_amdgcn_wave_barrier();
; __global__ void __launch_bounds__(512, 2) mega_fwd(Args a) {
;     ...
;             if (r < 1024) { transpose_item(a.in[10], 2048, 1024, Gwo, scr, r, lane); continue; } r -= 1024;
.LBB0_34:
	s_andn2_saveexec_b64 s[6:7], s[14:15]
	s_cbranch_execz .LBB0_36
	v_add_u32_e32 v2, 0x1400, v30
	v_and_b32_e32 v21, 0x1ffc0, v2
	v_and_b32_e32 v23, 0x3e0, v29
	v_or_b32_e32 v51, v21, v24
	v_lshlrev_b32_e32 v2, 2, v23
	v_lshl_add_u64 v[52:53], v[12:13], 0, v[2:3]
	v_lshlrev_b32_e32 v2, 12, v51
	v_lshl_add_u64 v[80:81], v[52:53], 0, v[2:3]
	v_add_co_u32_e32 v56, vcc, 0x8000, v80
	v_or_b32_e32 v51, v23, v24
	s_nop 0
	v_addc_co_u32_e32 v57, vcc, 0, v81, vcc
	v_add_co_u32_e32 v60, vcc, 0x10000, v80
	global_load_dwordx4 v[52:55], v[80:81], off nt
	s_nop 0
	global_load_dwordx4 v[56:59], v[56:57], off nt
	v_addc_co_u32_e32 v61, vcc, 0, v81, vcc
	v_add_co_u32_e32 v64, vcc, 0x18000, v80
	v_lshlrev_b32_e32 v2, 1, v21
	s_nop 0
	v_addc_co_u32_e32 v65, vcc, 0, v81, vcc
	v_add_co_u32_e32 v68, vcc, 0x20000, v80
	global_load_dwordx4 v[60:63], v[60:61], off nt
	s_nop 0
	global_load_dwordx4 v[64:67], v[64:65], off nt
	v_addc_co_u32_e32 v69, vcc, 0, v81, vcc
	v_add_co_u32_e32 v72, vcc, 0x28000, v80
	s_nop 1
	v_addc_co_u32_e32 v73, vcc, 0, v81, vcc
	global_load_dwordx4 v[68:71], v[68:69], off nt
	s_nop 0
	global_load_dwordx4 v[72:75], v[72:73], off nt
	v_add_co_u32_e32 v76, vcc, 0x30000, v80
	s_nop 1
	v_addc_co_u32_e32 v77, vcc, 0, v81, vcc
	global_load_dwordx4 v[76:79], v[76:77], off nt
	v_add_co_u32_e32 v80, vcc, 0x38000, v80
	s_nop 1
	v_addc_co_u32_e32 v81, vcc, 0, v81, vcc
	global_load_dwordx4 v[80:83], v[80:81], off nt
	s_waitcnt vmcnt(7)
	ds_write2_b32 v31, v52, v53 offset1:1
	ds_write2_b32 v31, v54, v55 offset0:2 offset1:3
	s_waitcnt vmcnt(6)
	ds_write2_b32 v32, v56, v57 offset1:1
	ds_write2_b32 v33, v58, v59 offset1:1
	s_waitcnt vmcnt(5)
	ds_write2_b32 v34, v60, v61 offset1:1
	ds_write2_b32 v35, v62, v63 offset1:1
	s_waitcnt vmcnt(4)
	ds_write2_b32 v36, v64, v65 offset1:1
	ds_write2_b32 v37, v66, v67 offset1:1
	s_waitcnt vmcnt(3)
	ds_write2_b32 v38, v68, v69 offset1:1
	ds_write2_b32 v39, v70, v71 offset1:1
	s_waitcnt vmcnt(2)
	ds_write2_b32 v40, v72, v73 offset1:1
	ds_write2_b32 v41, v74, v75 offset1:1
	s_waitcnt vmcnt(1)
	ds_write2_b32 v42, v76, v77 offset1:1
	ds_write2_b32 v43, v78, v79 offset1:1
	s_waitcnt vmcnt(0)
	ds_write2_b32 v44, v80, v81 offset1:1
	ds_write2_b32 v45, v82, v83 offset1:1
	ds_read2_b32 v[52:53], v28 offset1:33
	s_waitcnt lgkmcnt(0)
	v_cvt_pk_bf16_f32 v52, v52, v53
	ds_read2_b32 v[54:55], v28 offset0:66 offset1:99
	s_waitcnt lgkmcnt(0)
	v_cvt_pk_bf16_f32 v53, v54, v55
	ds_read2_b32 v[54:55], v28 offset0:132 offset1:165
	v_lshl_add_u64 v[58:59], v[14:15], 0, v[2:3]
	v_lshlrev_b32_e32 v2, 12, v51
	s_waitcnt lgkmcnt(0)
	v_cvt_pk_bf16_f32 v54, v54, v55
	ds_read2_b32 v[56:57], v28 offset0:198 offset1:231
	s_waitcnt lgkmcnt(0)
	v_cvt_pk_bf16_f32 v55, v56, v57
	v_lshl_add_u64 v[60:61], v[58:59], 0, v[2:3]
	ds_read2_b32 v[56:57], v28 offset0:8 offset1:41
	global_store_dwordx4 v[60:61], v[52:55], off
	v_or_b32_e32 v2, v23, v25
	v_lshlrev_b32_e32 v2, 12, v2
	s_waitcnt lgkmcnt(0)
	v_cvt_pk_bf16_f32 v52, v56, v57
	ds_read2_b32 v[54:55], v28 offset0:74 offset1:107
	s_waitcnt lgkmcnt(0)
	v_cvt_pk_bf16_f32 v53, v54, v55
	ds_read2_b32 v[54:55], v28 offset0:140 offset1:173
	s_waitcnt lgkmcnt(0)
	v_cvt_pk_bf16_f32 v54, v54, v55
	ds_read2_b32 v[56:57], v28 offset0:206 offset1:239
	s_waitcnt lgkmcnt(0)
	v_cvt_pk_bf16_f32 v55, v56, v57
	v_lshl_add_u64 v[60:61], v[58:59], 0, v[2:3]
	ds_read2_b32 v[56:57], v28 offset0:16 offset1:49
	global_store_dwordx4 v[60:61], v[52:55], off
	v_or_b32_e32 v2, v23, v26
	v_lshlrev_b32_e32 v2, 12, v2
	s_waitcnt lgkmcnt(0)
	v_cvt_pk_bf16_f32 v52, v56, v57
	ds_read2_b32 v[54:55], v28 offset0:82 offset1:115
	s_waitcnt lgkmcnt(0)
	v_cvt_pk_bf16_f32 v53, v54, v55
	ds_read2_b32 v[54:55], v28 offset0:148 offset1:181
	s_waitcnt lgkmcnt(0)
	v_cvt_pk_bf16_f32 v54, v54, v55
	ds_read2_b32 v[56:57], v28 offset0:214 offset1:247
	s_waitcnt lgkmcnt(0)
	v_cvt_pk_bf16_f32 v55, v56, v57
	v_lshl_add_u64 v[60:61], v[58:59], 0, v[2:3]
	ds_read2_b32 v[56:57], v28 offset0:24 offset1:57
	global_store_dwordx4 v[60:61], v[52:55], off
	v_or_b32_e32 v2, v23, v27
	v_lshlrev_b32_e32 v2, 12, v2
	s_waitcnt lgkmcnt(0)
	v_cvt_pk_bf16_f32 v52, v56, v57
	ds_read2_b32 v[54:55], v28 offset0:90 offset1:123
	s_waitcnt lgkmcnt(0)
	v_cvt_pk_bf16_f32 v53, v54, v55
	ds_read2_b32 v[54:55], v28 offset0:156 offset1:189
	s_waitcnt lgkmcnt(0)
	v_cvt_pk_bf16_f32 v54, v54, v55
	ds_read2_b32 v[56:57], v28 offset0:222 offset1:255
	s_waitcnt lgkmcnt(0)
	v_cvt_pk_bf16_f32 v55, v56, v57
	v_lshl_add_u64 v[56:57], v[58:59], 0, v[2:3]
	global_store_dwordx4 v[56:57], v[52:55], off

; __device__ __forceinline__ unsigned cvt_pk_bf16(float lo, float hi) { unsigned r; asm volatile("v_cvt_pk_bf16_f32 %0, %1, %2" : "=v"(r) : "v"(lo), "v"(hi)); return r; }
; #define LAS __attribute__((address_space(3)))
; __device__ __forceinline__ void transpose_item(const float* W, int K, int N, bf16_t* WT, LAS float* scr, int item, int lane) {
;     const int nblk = N / 32, kb = item / nblk, nb = item % nblk, k0 = 64 * kb, n0 = 32 * nb;
;     f32x4 tv[8];
; #pragma unroll
;     for (int i = 0; i < 8; ++i) tv[i] = *(const f32x4*)(W + (size_t)(k0 + 8 * i + (lane >> 3)) * N + n0 + 4 * (lane & 7));
; #pragma unroll
;     for (int i = 0; i < 8; ++i) { LAS float* d = scr + (8 * i + (lane >> 3)) * 33 + 4 * (lane & 7); d[0] = tv[i][0]; d[1] = tv[i][1]; d[2] = tv[i][2]; d[3] = tv[i][3]; }
;     __builtin_amdgcn_wave_barrier();
;     const int c = lane & 7;
; #pragma unroll
;     for (int j = 0; j < 4; ++j) { const int n = (lane >> 3) + 8 * j; const LAS float* s = scr + (8 * c) * 33 + n;
;         u32x4 o; o.x = cvt_pk_bf16(s[0 * 33], s[1 * 33]); o.y = cvt_pk_bf16(s[2 * 33], s[3 * 33]); o.z = cvt_pk_bf16(s[4 * 33], s[5 * 33]); o.w = cvt_pk_bf16(s[6 * 33], s[7 * 33]);
;         *(u32x4*)(WT + (size_t)(n0 + n) * K + k0 + 8 * c) = o; }
;     __builtin_amdgcn_wave_barrier();
; __global__ void __launch_bounds__(512, 2) mega_fwd(Args a) {
;     ...
;             if (r < 2048) { transpose_item(a.in[6], 1024, 4096, Win, scr, r, lane); continue; } r -= 2048;
.LBB0_37:
	s_andn2_saveexec_b64 s[2:3], s[2:3]
	s_cbranch_execz .LBB0_18
	v_ashrrev_i32_e32 v2, 31, v1
	v_lshrrev_b32_e32 v2, 25, v2
	v_add_u32_e32 v2, v1, v2
	v_ashrrev_i32_e32 v2, 7, v2
	v_lshlrev_b32_e32 v84, 6, v2
	v_lshlrev_b32_e32 v2, 12, v2
	v_or_b32_e32 v80, v84, v24
	v_sub_u32_e32 v86, v29, v2
	v_or_b32_e32 v54, 8, v80
	v_or_b32_e32 v60, 16, v80
	v_or_b32_e32 v62, 24, v80
	v_or_b32_e32 v68, 32, v80
	v_or_b32_e32 v70, 40, v80
	v_ashrrev_i32_e32 v87, 31, v86
	v_ashrrev_i32_e32 v81, 31, v80
	v_ashrrev_i32_e32 v55, 31, v54
	v_ashrrev_i32_e32 v61, 31, v60
	v_ashrrev_i32_e32 v63, 31, v62
	v_ashrrev_i32_e32 v69, 31, v68
	v_ashrrev_i32_e32 v71, 31, v70
	v_lshl_add_u64 v[82:83], v[86:87], 2, v[16:17]
	v_lshlrev_b64 v[52:53], 14, v[80:81]
	v_lshlrev_b64 v[54:55], 14, v[54:55]
	v_lshlrev_b64 v[60:61], 14, v[60:61]
	v_lshlrev_b64 v[62:63], 14, v[62:63]
	v_lshlrev_b64 v[68:69], 14, v[68:69]
	v_lshlrev_b64 v[70:71], 14, v[70:71]
	v_lshl_add_u64 v[52:53], v[82:83], 0, v[52:53]
	v_lshl_add_u64 v[56:57], v[82:83], 0, v[54:55]
	v_lshl_add_u64 v[60:61], v[82:83], 0, v[60:61]
	v_lshl_add_u64 v[64:65], v[82:83], 0, v[62:63]
	v_lshl_add_u64 v[68:69], v[82:83], 0, v[68:69]
	v_lshl_add_u64 v[72:73], v[82:83], 0, v[70:71]
	global_load_dwordx4 v[52:55], v[52:53], off nt
	s_nop 0
	global_load_dwordx4 v[56:59], v[56:57], off nt
	s_nop 0
	global_load_dwordx4 v[60:63], v[60:61], off nt
	s_nop 0
	global_load_dwordx4 v[64:67], v[64:65], off nt
	s_nop 0
	global_load_dwordx4 v[68:71], v[68:69], off nt
	s_nop 0
	global_load_dwordx4 v[72:75], v[72:73], off nt
	v_or_b32_e32 v76, 48, v80
	v_ashrrev_i32_e32 v77, 31, v76
	v_lshlrev_b64 v[76:77], 14, v[76:77]
	v_or_b32_e32 v80, 56, v80
	v_lshl_add_u64 v[76:77], v[82:83], 0, v[76:77]
	v_ashrrev_i32_e32 v81, 31, v80
	global_load_dwordx4 v[76:79], v[76:77], off nt
	v_lshlrev_b64 v[80:81], 14, v[80:81]
	v_lshl_add_u64 v[80:81], v[82:83], 0, v[80:81]
	global_load_dwordx4 v[80:83], v[80:81], off nt
	v_ashrrev_i32_e32 v85, 31, v84
	s_waitcnt vmcnt(7)
	ds_write2_b32 v31, v52, v53 offset1:1
	ds_write2_b32 v31, v54, v55 offset0:2 offset1:3
	s_waitcnt vmcnt(6)
	ds_write2_b32 v32, v56, v57 offset1:1
	ds_write2_b32 v33, v58, v59 offset1:1
	s_waitcnt vmcnt(5)
	ds_write2_b32 v34, v60, v61 offset1:1
	ds_write2_b32 v35, v62, v63 offset1:1
	s_waitcnt vmcnt(4)
	ds_write2_b32 v36, v64, v65 offset1:1
	ds_write2_b32 v37, v66, v67 offset1:1
	s_waitcnt vmcnt(3)
	ds_write2_b32 v38, v68, v69 offset1:1
	ds_write2_b32 v39, v70, v71 offset1:1
	s_waitcnt vmcnt(2)
	ds_write2_b32 v40, v72, v73 offset1:1
	ds_write2_b32 v41, v74, v75 offset1:1
	s_waitcnt vmcnt(1)
	ds_write2_b32 v42, v76, v77 offset1:1
	ds_write2_b32 v43, v78, v79 offset1:1
	s_waitcnt vmcnt(0)
	ds_write2_b32 v44, v80, v81 offset1:1
	ds_write2_b32 v45, v82, v83 offset1:1
	v_add_u32_e32 v60, v86, v24
	ds_read2_b32 v[52:53], v28 offset1:33
	v_ashrrev_i32_e32 v61, 31, v60
	s_waitcnt lgkmcnt(0)
	v_cvt_pk_bf16_f32 v52, v52, v53
	ds_read2_b32 v[54:55], v28 offset0:66 offset1:99
	v_lshl_add_u64 v[58:59], v[84:85], 1, v[18:19]
	v_lshlrev_b64 v[62:63], 11, v[60:61]
	s_waitcnt lgkmcnt(0)
	v_cvt_pk_bf16_f32 v53, v54, v55
	ds_read2_b32 v[54:55], v28 offset0:132 offset1:165
	v_lshl_add_u64 v[62:63], v[58:59], 0, v[62:63]
	s_waitcnt lgkmcnt(0)
	v_cvt_pk_bf16_f32 v54, v54, v55
	ds_read2_b32 v[56:57], v28 offset0:198 offset1:231
	s_waitcnt lgkmcnt(0)
	v_cvt_pk_bf16_f32 v55, v56, v57
	global_store_dwordx4 v[62:63], v[52:55], off
	v_add_u32_e32 v62, 8, v60
	v_ashrrev_i32_e32 v63, 31, v62
	ds_read2_b32 v[56:57], v28 offset0:8 offset1:41
	s_waitcnt lgkmcnt(0)
	v_cvt_pk_bf16_f32 v52, v56, v57
	ds_read2_b32 v[54:55], v28 offset0:74 offset1:107
	v_lshlrev_b64 v[62:63], 11, v[62:63]
	s_waitcnt lgkmcnt(0)
	v_cvt_pk_bf16_f32 v53, v54, v55
	ds_read2_b32 v[54:55], v28 offset0:140 offset1:173
	v_lshl_add_u64 v[62:63], v[58:59], 0, v[62:63]
	s_waitcnt lgkmcnt(0)
	v_cvt_pk_bf16_f32 v54, v54, v55
	ds_read2_b32 v[56:57], v28 offset0:206 offset1:239
	s_waitcnt lgkmcnt(0)
	v_cvt_pk_bf16_f32 v55, v56, v57
	global_store_dwordx4 v[62:63], v[52:55], off
	v_add_u32_e32 v62, 16, v60
	ds_read2_b32 v[56:57], v28 offset0:16 offset1:49
	s_waitcnt lgkmcnt(0)
	v_cvt_pk_bf16_f32 v52, v56, v57
	ds_read2_b32 v[54:55], v28 offset0:82 offset1:115
	v_ashrrev_i32_e32 v63, 31, v62
	s_waitcnt lgkmcnt(0)
	v_cvt_pk_bf16_f32 v53, v54, v55
	ds_read2_b32 v[54:55], v28 offset0:148 offset1:181
	v_lshlrev_b64 v[62:63], 11, v[62:63]
	s_waitcnt lgkmcnt(0)
	v_cvt_pk_bf16_f32 v54, v54, v55
	ds_read2_b32 v[56:57], v28 offset0:214 offset1:247
	s_waitcnt lgkmcnt(0)
	v_cvt_pk_bf16_f32 v55, v56, v57
	v_lshl_add_u64 v[62:63], v[58:59], 0, v[62:63]
	ds_read2_b32 v[56:57], v28 offset0:24 offset1:57
	global_store_dwordx4 v[62:63], v[52:55], off
	v_add_u32_e32 v60, 24, v60
	v_ashrrev_i32_e32 v61, 31, v60
	s_waitcnt lgkmcnt(0)
	v_cvt_pk_bf16_f32 v52, v56, v57
	ds_read2_b32 v[54:55], v28 offset0:90 offset1:123
	s_waitcnt lgkmcnt(0)
	v_cvt_pk_bf16_f32 v53, v54, v55
	ds_read2_b32 v[54:55], v28 offset0:156 offset1:189
	s_waitcnt lgkmcnt(0)
	v_cvt_pk_bf16_f32 v54, v54, v55
	ds_read2_b32 v[56:57], v28 offset0:222 offset1:255
	v_lshlrev_b64 v[60:61], 11, v[60:61]
	s_waitcnt lgkmcnt(0)
	v_cvt_pk_bf16_f32 v55, v56, v57
	v_lshl_add_u64 v[56:57], v[58:59], 0, v[60:61]
	global_store_dwordx4 v[56:57], v[52:55], off
	s_branch .LBB0_18

; __device__ __forceinline__ unsigned cvt_pk_bf16(float lo, float hi) { unsigned r; asm volatile("v_cvt_pk_bf16_f32 %0, %1, %2" : "=v"(r) : "v"(lo), "v"(hi)); return r; }
; __device__ __forceinline__ void norm_phase(const float* src_l, const float* src_c, int nrows, const float* modl, int shoff, int scoff, bf16_t* xl) {
;     ...
;     for (int r = gw; r < nrows; r += NGW) {
;         const bool lat = r < MLAT; const int cond = lat ? (r >> 13) : 8;
;         const float* xr = lat ? src_l + (size_t)r * DM : src_c + (size_t)(r - MLAT) * DM;
;         const float* mp = modl + cond * 6144;
;         f32x4 v[4]; float s = 0.f;
; #pragma unroll
;         for (int j = 0; j < 4; ++j) { v[j] = *(const f32x4*)(xr + 4 * lane + 256 * j); s += v[j][0] * v[j][0] + v[j][1] * v[j][1] + v[j][2] * v[j][2] + v[j][3] * v[j][3]; }
;         const float rstd = rsqrtf(wave_sum(s) * (1.0f / DM) + EPS);
; #pragma unroll
;         for (int j = 0; j < 4; ++j) { const int col = 4 * lane + 256 * j; const f32x4 sc = *(const f32x4*)(mp + scoff + col), sh = *(const f32x4*)(mp + shoff + col);
;             const f32x4 o = v[j] * rstd * (sc + 1.0f) + sh; u32x2 w; w.x = cvt_pk_bf16(o[0], o[1]); w.y = cvt_pk_bf16(o[2], o[3]);
;             *(u32x2*)(xl + (size_t)r * DM + col) = w; }
;     }
.LBB0_56:
	s_or_b64 exec, exec, s[12:13]
	v_lshl_add_u64 v[18:19], v[18:19], 0, v[8:9]
	global_load_dwordx4 v[28:31], v[18:19], off nt
	global_load_dwordx4 v[32:35], v[18:19], off offset:1024 nt
	global_load_dwordx4 v[36:39], v[18:19], off offset:2048 nt
	global_load_dwordx4 v[40:43], v[18:19], off offset:3072 nt
	v_min_i32_e32 v2, 0x10000, v0
	v_ashrrev_i32_e32 v2, 13, v2
	v_mul_i32_i24_e32 v18, 0x1800, v2
	v_ashrrev_i32_e32 v19, 31, v18
	v_lshl_add_u64 v[18:19], v[18:19], 2, s[54:55]
	v_lshl_add_u64 v[52:53], v[18:19], 0, s[10:11]
	v_lshl_add_u64 v[44:45], v[52:53], 0, v[8:9]
	global_load_dwordx4 v[44:47], v[44:45], off
	v_lshl_add_u64 v[54:55], v[18:19], 0, v[8:9]
	global_load_dwordx4 v[48:51], v[54:55], off
	v_lshl_add_u64 v[70:71], v[52:53], 0, v[10:11]
	global_load_dwordx4 v[72:75], v[70:71], off
	global_load_dwordx4 v[76:79], v[54:55], off offset:1024
	v_lshl_add_u64 v[70:71], v[52:53], 0, v[12:13]
	global_load_dwordx4 v[80:83], v[70:71], off
	global_load_dwordx4 v[84:87], v[54:55], off offset:2048
	v_lshl_add_u64 v[70:71], v[52:53], 0, v[14:15]
	global_load_dwordx4 v[88:91], v[70:71], off
	global_load_dwordx4 v[92:95], v[54:55], off offset:3072
	v_lshlrev_b64 v[16:17], 11, v[16:17]
	v_lshl_add_u64 v[0:1], v[0:1], 0, s[78:79]
	v_lshl_add_u64 v[6:7], v[6:7], 0, s[6:7]
	s_waitcnt vmcnt(11)
	v_mov_b32_e32 v56, v29
	s_waitcnt vmcnt(10)
	v_mov_b32_e32 v57, v33
	v_mov_b32_e32 v18, v28
	v_mov_b32_e32 v19, v32
	s_waitcnt vmcnt(9)
	v_mov_b32_e32 v64, v37
	s_waitcnt vmcnt(8)
	v_mov_b32_e32 v65, v41
	v_pk_mul_f32 v[56:57], v[56:57], v[56:57]
	v_mov_b32_e32 v58, v30
	v_mov_b32_e32 v59, v34
	v_mov_b32_e32 v62, v36
	v_mov_b32_e32 v63, v40
	v_pk_mul_f32 v[64:65], v[64:65], v[64:65]
	v_pk_fma_f32 v[18:19], v[18:19], v[18:19], v[56:57]
	v_mov_b32_e32 v60, v31
	v_mov_b32_e32 v61, v35
	v_mov_b32_e32 v66, v38
	v_mov_b32_e32 v67, v42
	v_pk_fma_f32 v[56:57], v[62:63], v[62:63], v[64:65]
	v_pk_fma_f32 v[18:19], v[58:59], v[58:59], v[18:19]
	v_mov_b32_e32 v68, v39
	v_mov_b32_e32 v69, v43
	v_pk_fma_f32 v[56:57], v[66:67], v[66:67], v[56:57]
	v_pk_fma_f32 v[18:19], v[60:61], v[60:61], v[18:19]
	v_pk_fma_f32 v[56:57], v[68:69], v[68:69], v[56:57]
	v_add_f32_e32 v2, v18, v19
	v_add_f32_e32 v2, v2, v56
	v_add_f32_e32 v2, v2, v57
	ds_bpermute_b32 v18, v20, v2
	v_lshl_add_u64 v[56:57], v[4:5], 0, v[16:17]
	s_waitcnt vmcnt(7)
	v_pk_add_f32 v[44:45], v[44:45], 1.0 op_sel_hi:[1,0]
	s_waitcnt lgkmcnt(0)
	v_add_f32_e32 v2, v2, v18
	ds_bpermute_b32 v18, v21, v2
	s_waitcnt lgkmcnt(0)
	v_add_f32_e32 v2, v2, v18
	ds_bpermute_b32 v18, v22, v2
	s_waitcnt lgkmcnt(0)
	v_add_f32_e32 v2, v2, v18
	ds_bpermute_b32 v18, v23, v2
	s_waitcnt lgkmcnt(0)
	v_add_f32_e32 v2, v2, v18
	ds_bpermute_b32 v18, v24, v2
	s_waitcnt lgkmcnt(0)
	v_add_f32_e32 v2, v2, v18
	ds_bpermute_b32 v18, v25, v2
	s_waitcnt lgkmcnt(0)
	v_add_f32_e32 v2, v2, v18
	v_fmamk_f32 v2, v2, 0x3a800000, v26
	v_mul_f32_e32 v16, 0x4b800000, v2
	v_cmp_gt_f32_e32 vcc, s15, v2
	v_pk_add_f32 v[18:19], v[46:47], 1.0 op_sel_hi:[1,0]
	s_nop 0
	v_cndmask_b32_e32 v2, v2, v16, vcc
	v_rsq_f32_e32 v2, v2
	v_lshl_add_u64 v[16:17], v[52:53], 0, v[10:11]
	v_mul_f32_e32 v27, 0x45800000, v2
	v_cndmask_b32_e32 v2, v2, v27, vcc
	v_pk_mul_f32 v[28:29], v[28:29], v[2:3] op_sel_hi:[1,0]
	v_pk_mul_f32 v[30:31], v[30:31], v[2:3] op_sel_hi:[1,0]
	s_waitcnt vmcnt(6)
	v_pk_fma_f32 v[28:29], v[44:45], v[28:29], v[48:49]
	v_pk_fma_f32 v[18:19], v[18:19], v[30:31], v[50:51]
	v_cvt_pk_bf16_f32 v28, v28, v29
	v_pk_mul_f32 v[32:33], v[32:33], v[2:3] op_sel_hi:[1,0]
	v_cvt_pk_bf16_f32 v29, v18, v19
	global_store_dwordx2 v[56:57], v[28:29], off
	v_pk_mul_f32 v[34:35], v[34:35], v[2:3] op_sel_hi:[1,0]
	v_lshl_add_u64 v[44:45], v[52:53], 0, v[12:13]
	v_cmp_lt_i32_e32 vcc, s26, v0
	s_or_b64 s[8:9], vcc, s[8:9]
	s_waitcnt vmcnt(6)
	v_pk_add_f32 v[16:17], v[72:73], 1.0 op_sel_hi:[1,0]
	v_pk_add_f32 v[18:19], v[74:75], 1.0 op_sel_hi:[1,0]
	s_waitcnt vmcnt(5)
	v_pk_fma_f32 v[16:17], v[16:17], v[32:33], v[76:77]
	v_pk_fma_f32 v[18:19], v[18:19], v[34:35], v[78:79]
	v_cvt_pk_bf16_f32 v16, v16, v17
	v_pk_mul_f32 v[34:35], v[36:37], v[2:3] op_sel_hi:[1,0]
	v_cvt_pk_bf16_f32 v17, v18, v19
	global_store_dwordx2 v[56:57], v[16:17], off offset:512
	v_pk_mul_f32 v[36:37], v[38:39], v[2:3] op_sel_hi:[1,0]
	v_lshl_add_u64 v[32:33], v[52:53], 0, v[14:15]
	s_waitcnt vmcnt(5)
	v_pk_add_f32 v[16:17], v[80:81], 1.0 op_sel_hi:[1,0]
	v_pk_add_f32 v[18:19], v[82:83], 1.0 op_sel_hi:[1,0]
	s_waitcnt vmcnt(4)
	v_pk_fma_f32 v[16:17], v[16:17], v[34:35], v[84:85]
	v_pk_fma_f32 v[18:19], v[18:19], v[36:37], v[86:87]
	v_cvt_pk_bf16_f32 v16, v16, v17
	v_pk_mul_f32 v[34:35], v[42:43], v[2:3] op_sel_hi:[1,0]
	v_cvt_pk_bf16_f32 v17, v18, v19
	global_store_dwordx2 v[56:57], v[16:17], off offset:1024
	v_pk_mul_f32 v[32:33], v[40:41], v[2:3] op_sel_hi:[1,0]
	s_waitcnt vmcnt(4)
	v_pk_add_f32 v[16:17], v[88:89], 1.0 op_sel_hi:[1,0]
	v_pk_add_f32 v[18:19], v[90:91], 1.0 op_sel_hi:[1,0]
	s_waitcnt vmcnt(3)
	v_pk_fma_f32 v[16:17], v[32:33], v[16:17], v[92:93]
	v_pk_fma_f32 v[18:19], v[34:35], v[18:19], v[94:95]
	v_cvt_pk_bf16_f32 v16, v16, v17
	s_nop 0
	v_cvt_pk_bf16_f32 v17, v18, v19
	global_store_dwordx2 v[56:57], v[16:17], off offset:1536
	s_andn2_b64 exec, exec, s[8:9]
	s_cbranch_execz .LBB0_59

; __device__ __forceinline__ int tid_fresh() { int t = (int)threadIdx.x; asm volatile("" : "+v"(t)); return t; }
; __device__ __forceinline__ float bflo(unsigned w) { return __uint_as_float(w << 16); }
; __device__ __forceinline__ float bfhi(unsigned w) { return __uint_as_float(w & 0xffff0000u); }
; __device__ __forceinline__ void final_norm_phase(const bf16_t* hb, float* out, const float* g) {
;     const int lane = tid_fresh() & 63, gw = blockIdx.x * 8 + (tid_fresh() >> 6), NGW = gridDim.x * 8;
;     for (int r = gw; r < MLAT; r += NGW) {
;         const bf16_t* xr = hb + (size_t)r * DM + 8 * lane; const u32x4 w0 = *(const u32x4*)(xr), w1 = *(const u32x4*)(xr + 512);
;         float v[16]; float s = 0.f;
; #pragma unroll
;         for (int e = 0; e < 4; ++e) { v[2 * e] = bflo(w0[e]); v[2 * e + 1] = bfhi(w0[e]); v[8 + 2 * e] = bflo(w1[e]); v[8 + 2 * e + 1] = bfhi(w1[e]); }
; #pragma unroll
;         for (int e = 0; e < 16; ++e) s += v[e] * v[e];
;         const float rstd = rsqrtf(wave_sum(s) * (1.0f / DM) + EPS);
; #pragma unroll
;         for (int h = 0; h < 2; ++h) { const int col = 8 * lane + 512 * h; const f32x4 g0 = *(const f32x4*)(g + col), g1 = *(const f32x4*)(g + col + 4);
;             f32x4 o0, o1;
; #pragma unroll
;             for (int e = 0; e < 4; ++e) { o0[e] = v[8 * h + e] * rstd * g0[e]; o1[e] = v[8 * h + 4 + e] * rstd * g1[e]; }
;             *(f32x4*)(out + (size_t)r * DM + col) = o0; *(f32x4*)(out + (size_t)r * DM + col + 4) = o1; }
;     }
; }
.LBB0_1229:
	s_or_b64 exec, exec, s[2:3]
	v_mov_b32_e32 v4, v204
	s_waitcnt lgkmcnt(0)
	s_barrier
	v_readlane_b32 s0, v254, 6
	v_ashrrev_i32_e32 v0, 6, v204
	s_nop 0
	v_add_u32_e32 v0, s0, v0
	s_mov_b32 s0, 0x10000
	v_cmp_gt_i32_e32 vcc, s0, v0
	s_and_saveexec_b64 s[0:1], vcc
	v_readlane_b32 s2, v254, 21
	v_readlane_b32 s3, v254, 22
	s_cbranch_execz .LBB0_1232
	s_load_dwordx2 s[0:1], s[2:3], 0xb0
	v_ashrrev_i32_e32 v1, 31, v0
	v_lshlrev_b64 v[6:7], 11, v[0:1]
	v_and_b32_e32 v8, 63, v4
	v_lshlrev_b32_e32 v2, 5, v4
	v_lshl_or_b32 v6, v8, 4, v6
	v_mov_b32_e32 v3, 0
	v_and_b32_e32 v2, 0x7e0, v2
	v_lshl_add_u64 v[4:5], s[54:55], 0, v[6:7]
	v_lshlrev_b64 v[6:7], 12, v[0:1]
	s_waitcnt lgkmcnt(0)
	v_lshl_add_u64 v[2:3], s[0:1], 0, v[2:3]
	s_mov_b64 s[0:1], 0x34c00400
	s_ashr_i32 s21, s20, 31
	v_lshl_or_b32 v6, v8, 5, v6
	v_lshl_add_u64 v[4:5], v[4:5], 0, s[0:1]
	s_lshl_b64 s[0:1], s[20:21], 11
	v_lshl_add_u64 v[6:7], s[52:53], 0, v[6:7]
	s_lshl_b64 s[2:3], s[20:21], 12
	s_mov_b64 s[4:5], 0
	v_mov_b32_e32 v1, 0x358637bd
	s_mov_b32 s6, 0x800000
	s_mov_b32 s7, 0xffff
	global_load_dwordx4 v[48:51], v[2:3], off
	global_load_dwordx4 v[52:55], v[2:3], off offset:16
	global_load_dwordx4 v[56:59], v[2:3], off offset:2048
	global_load_dwordx4 v[60:63], v[2:3], off offset:2064
	global_load_dwordx4 v[64:67], v[4:5], off offset:-1024 nt
	global_load_dwordx4 v[68:71], v[4:5], off nt
	v_lshl_add_u64 v[4:5], v[4:5], 0, s[0:1]
	s_waitcnt vmcnt(0)
	s_branch .Lfn_body
.LBB0_1231:
	s_waitcnt vmcnt(4)
.Lfn_body:
	v_add_u32_e32 v0, s20, v0
	v_lshlrev_b32_e32 v26, 16, v64
	v_and_b32_e32 v27, 0xffff0000, v64
	v_lshlrev_b32_e32 v8, 16, v65
	v_and_b32_e32 v9, 0xffff0000, v65
	v_pk_mul_f32 v[36:37], v[26:27], v[26:27]
	v_pk_mul_f32 v[38:39], v[8:9], v[8:9]
	v_add_f32_e32 v36, v36, v37
	v_lshlrev_b32_e32 v24, 16, v66
	v_and_b32_e32 v25, 0xffff0000, v66
	v_add_f32_e32 v36, v38, v36
	v_lshlrev_b32_e32 v32, 16, v68
	v_and_b32_e32 v33, 0xffff0000, v68
	v_lshlrev_b32_e32 v34, 16, v69
	v_and_b32_e32 v35, 0xffff0000, v69
	v_pk_mul_f32 v[12:13], v[24:25], v[24:25]
	v_add_f32_e32 v36, v39, v36
	v_lshlrev_b32_e32 v10, 16, v67
	v_and_b32_e32 v11, 0xffff0000, v67
	v_add_f32_e32 v12, v12, v36
	v_lshlrev_b32_e32 v28, 16, v70
	v_and_b32_e32 v29, 0xffff0000, v70
	v_lshlrev_b32_e32 v30, 16, v71
	v_and_b32_e32 v31, 0xffff0000, v71
	global_load_dwordx4 v[64:67], v[4:5], off offset:-1024 nt
	global_load_dwordx4 v[68:71], v[4:5], off nt
	v_lshl_add_u64 v[4:5], v[4:5], 0, s[0:1]
	v_pk_mul_f32 v[14:15], v[10:11], v[10:11]
	v_add_f32_e32 v12, v13, v12
	v_add_f32_e32 v12, v14, v12
	v_pk_mul_f32 v[44:45], v[32:33], v[32:33]
	v_add_f32_e32 v12, v15, v12
	v_add_f32_e32 v12, v44, v12
	v_pk_mul_f32 v[46:47], v[34:35], v[34:35]
	v_add_f32_e32 v12, v45, v12
	v_add_f32_e32 v12, v46, v12
	v_pk_mul_f32 v[40:41], v[28:29], v[28:29]
	v_add_f32_e32 v12, v47, v12
	v_add_f32_e32 v12, v40, v12
	v_pk_mul_f32 v[42:43], v[30:31], v[30:31]
	v_add_f32_e32 v12, v41, v12
	v_add_f32_e32 v12, v42, v12
	v_add_f32_e32 v12, v43, v12
	ds_bpermute_b32 v13, v205, v12
	s_waitcnt lgkmcnt(0)
	v_add_f32_e32 v12, v12, v13
	ds_bpermute_b32 v13, v206, v12
	s_waitcnt lgkmcnt(0)
	v_add_f32_e32 v12, v12, v13
	ds_bpermute_b32 v13, v207, v12
	s_waitcnt lgkmcnt(0)
	v_add_f32_e32 v12, v12, v13
	ds_bpermute_b32 v13, v208, v12
	s_waitcnt lgkmcnt(0)
	v_add_f32_e32 v12, v12, v13
	ds_bpermute_b32 v13, v209, v12
	s_waitcnt lgkmcnt(0)
	v_add_f32_e32 v12, v12, v13
	ds_bpermute_b32 v13, v210, v12
	s_waitcnt lgkmcnt(0)
	v_add_f32_e32 v12, v12, v13
	v_fmamk_f32 v12, v12, 0x3a800000, v1
	v_mul_f32_e32 v13, 0x4b800000, v12
	v_cmp_gt_f32_e32 vcc, s6, v12
	s_nop 1
	v_cndmask_b32_e32 v12, v12, v13, vcc
	v_rsq_f32_e32 v12, v12
	s_nop 0
	v_mul_f32_e32 v13, 0x45800000, v12
	v_cndmask_b32_e32 v36, v12, v13, vcc
	v_pk_mul_f32 v[12:13], v[36:37], v[26:27] op_sel_hi:[0,1]
	v_pk_mul_f32 v[8:9], v[36:37], v[8:9] op_sel_hi:[0,1]
	v_pk_mul_f32 v[24:25], v[36:37], v[24:25] op_sel_hi:[0,1]
	v_pk_mul_f32 v[14:15], v[36:37], v[10:11] op_sel_hi:[0,1]
	v_pk_mul_f32 v[10:11], v[50:51], v[8:9]
	v_pk_mul_f32 v[8:9], v[48:49], v[12:13]
	v_pk_mul_f32 v[14:15], v[54:55], v[14:15]
	v_pk_mul_f32 v[12:13], v[52:53], v[24:25]
	global_store_dwordx4 v[6:7], v[8:11], off
	global_store_dwordx4 v[6:7], v[12:15], off offset:16
	s_nop 0
	v_pk_mul_f32 v[16:17], v[36:37], v[34:35] op_sel_hi:[0,1]
	v_pk_mul_f32 v[18:19], v[36:37], v[32:33] op_sel_hi:[0,1]
	v_cmp_lt_i32_e32 vcc, s7, v0
	v_pk_mul_f32 v[20:21], v[36:37], v[30:31] op_sel_hi:[0,1]
	v_pk_mul_f32 v[22:23], v[36:37], v[28:29] op_sel_hi:[0,1]
	s_or_b64 s[4:5], vcc, s[4:5]
	v_pk_mul_f32 v[8:9], v[56:57], v[18:19]
	v_pk_mul_f32 v[10:11], v[58:59], v[16:17]
	v_pk_mul_f32 v[12:13], v[60:61], v[22:23]
	v_pk_mul_f32 v[14:15], v[62:63], v[20:21]
	global_store_dwordx4 v[6:7], v[8:11], off offset:2048
	global_store_dwordx4 v[6:7], v[12:15], off offset:2064
	v_lshl_add_u64 v[6:7], v[6:7], 0, s[2:3]
	s_andn2_b64 exec, exec, s[4:5]
	s_cbranch_execnz .LBB0_1231
